# fused the depthwise conv3+bias+SiLU pass into the up-proj (value half) GEMM epilogue in fp32: removes one full read+write pass over the gate tensor per layer
# speedup vs baseline: 1.0110x; 1.0110x over previous
; DI int otid() { int t = threadIdx.x; asm volatile("" : "+v"(t)); return t; }
; DI void conv_phase(const Params& p, int l) {
;   const u16* G = (const u16*)(p.ws + WS_G);
;   u16* GS = (u16*)(p.ws + WS_ACT);
;   const float* cw = p.conv_w + (size_t)l * 3 * DFF; const float* cb = p.conv_b + (size_t)l * DFF;
;   const int tid_ = otid();
;   constexpr int RUN = 16;
;   const int nitems = (T / RUN) * (DFF / 8);
;   for (int it = blockIdx.x * NTHR + tid_; it < nitems; it += gridDim.x * NTHR) {
;     const int rr = it / (DFF / 8), cg = it - rr * (DFF / 8);
;     const int t0 = rr * RUN, c0 = cg * 8;
;     const u16* gp = G + (size_t)t0 * DFF + c0;
; __global__ void __launch_bounds__(512) fwd_megakernel(Params p) {
;     ...
;     } else if (q == 3) {
;       norm_mod_phase(X, modl, 3072, 4096, H);
;       xcd_barrier(xb);
;     } else if (q == 4) {
;       conv_phase(p, l);
;       xcd_barrier(xb);
.LBB0_68:
	s_mul_i32 s0, s33, 0xab
	s_bfe_u32 s79, s0, 0x6000a
	s_mov_b64 s[84:85], s[66:67]
	s_mul_i32 s76, s79, -6
	v_readlane_b32 s60, v239, 2
	s_add_i32 s97, s76, s33
	v_readlane_b32 s61, v239, 3
	s_cmp_lt_u32 s33, 6
	s_mov_b64 s[36:37], s[60:61]
	s_cselect_b32 s1, s37, s53
	s_cselect_b32 s0, s36, s52
	v_writelane_b32 v237, s0, 60
	v_readlane_b32 s62, v239, 4
	v_readlane_b32 s63, v239, 5
	v_writelane_b32 v237, s1, 61
	s_mul_i32 s0, s79, 0x30000
	s_add_u32 s56, s88, s0
	s_addc_u32 s57, s89, 0
	s_cmp_lg_u32 s97, 0
	s_cselect_b64 s[76:77], -1, 0
	s_and_b64 vcc, exec, s[76:77]
	v_readlane_b32 s64, v239, 6
	v_readlane_b32 s65, v239, 7
	v_readlane_b32 s66, v239, 8
	v_readlane_b32 s67, v239, 9
	v_readlane_b32 s68, v239, 10
	v_readlane_b32 s69, v239, 11
	v_readlane_b32 s70, v239, 12
	v_readlane_b32 s71, v239, 13
	v_readlane_b32 s72, v239, 14
	v_readlane_b32 s73, v239, 15
	v_readlane_b32 s74, v239, 16
	v_readlane_b32 s75, v239, 17
	v_writelane_b32 v237, s33, 62
	s_cbranch_vccz .LBB0_91
	v_readlane_b32 s46, v237, 10
	s_cmp_lt_i32 s97, 3
	v_readlane_b32 s33, v237, 12
	v_readlane_b32 s47, v237, 11
	s_cbranch_scc1 .LBB0_92
	s_cmp_gt_i32 s97, 3
	s_mov_b64 s[66:67], s[84:85]
	s_movk_i32 s48, 0x1000
	s_movk_i32 s49, 0x2000
	s_movk_i32 s62, 0x3000
	s_mov_b32 s63, 0xffff
	s_mov_b32 s70, 0x3a800000
	s_cbranch_scc0 .LBB0_93
	s_mov_b64 s[20:21], 0
	s_cmp_eq_u32 s97, 4
	s_mov_b64 s[40:41], 0
	s_cbranch_scc0 .LBB0_94
	v_mov_b32_e32 v1, v169
	v_readlane_b32 s0, v239, 34
	s_nop 1
	v_add_u32_e32 v1, s0, v1
	s_mov_b32 s0, 0x80000000
	v_cmp_gt_i32_e32 vcc, s0, v1
	s_and_saveexec_b64 s[22:23], vcc
	s_cbranch_execz .LBB0_109
	s_mul_i32 s0, s79, 0x8400
	v_readlane_b32 s36, v238, 0
	v_readlane_b32 s37, v238, 1
	s_add_u32 s30, s36, s0
	v_readlane_b32 s38, v238, 2
	s_addc_u32 s31, s37, 0
	s_mul_i32 s0, s79, 0x2c00
	v_readlane_b32 s39, v238, 3
	s_add_u32 s36, s38, s0
	s_addc_u32 s37, s39, 0
	s_add_u32 s38, s30, 0x2c00
	v_readlane_b32 s40, v238, 4
	s_addc_u32 s39, s31, 0
	v_readlane_b32 s41, v238, 5
	v_readlane_b32 s42, v238, 6
	v_readlane_b32 s43, v238, 7
	s_add_u32 s40, s30, 0x5800
	s_addc_u32 s41, s31, 0
	s_mov_b64 s[42:43], 0
	s_branch .LBB0_75

; #define PG8_STAGE(bufoff, gbase, voff) do { _Pragma("unroll") for (int _i = 0; _i < 2; ++_i) \
;         __builtin_amdgcn_global_load_lds((const unsigned*)((const char*)(gbase) + (voff)[_i]), (PG8_LAS unsigned*)(lds + (bufoff) + ldsw + _i * 8192), 16, 0, 0); } while (0)
; #define PG8_LDA(dst, b, h) do { _Pragma("unroll") for (int m = 0; m < 4; ++m) _Pragma("unroll") for (int k = 0; k < 2; ++k) dst[m][k] = *(const PG8_LAS bf16x8*)(lds + PG8_SA(b, h) + aoff + m * 2048 + k * 1024); } while (0)
; #define PG8_LDB(dst, b, h) do { _Pragma("unroll") for (int n = 0; n < 2; ++n) _Pragma("unroll") for (int k = 0; k < 2; ++k) dst[n][k] = *(const PG8_LAS bf16x8*)(lds + PG8_SB(b, h) + boff + n * 2048 + k * 1024); } while (0)
; #define PG8_MMA(ai, bj, At, Bt) do { __builtin_amdgcn_s_setprio(1); _Pragma("unroll") for (int m = 0; m < 4; ++m) _Pragma("unroll") for (int n = 0; n < 2; ++n) _Pragma("unroll") for (int k = 0; k < 2; ++k) \
;         acc[ai][bj][m][n] = __builtin_amdgcn_mfma_f32_16x16x32_bf16(Bt[n][k], At[m][k], acc[ai][bj][m][n], 0, 0, 0); __builtin_amdgcn_s_setprio(0); } while (0)
; #define PG8_BAR __builtin_amdgcn_s_barrier()
; template <class Epi, class Sched, bool STAMP = false>
; __device__ __forceinline__ void gemm_phase(PG8_LAS unsigned char* lds, const Gemm g, const Sched& S, const Epi& E, unsigned long long* stamps) {
;     ...
;         for (int t = 0; t < nt; t += 2) {
;             const bool last = (t == nt - 2);
;             const char* a1 = cA + (size_t)(t + 1) * kstep;
;             const char* a2 = last ? nA : cA + (size_t)(t + 2) * kstep; const char* b2 = last ? nB : cB + (size_t)(t + 2) * kstep;
;             const char* a3 = a2 + kstep; const char* b3 = b2 + kstep;
;             if (last && has_next) S.a_ready(nxt);
;             PG8_LDB(B0, 0, 0); PG8_SCHED; PG8_LDA(At, 0, 0); PG8_STAGE(PG8_SA(1, 1), a1 + hstep, voffA);
;             PG8_WAIT_L(8); PG8_BAR; PG8_WAIT_L(0); PG8_MMA(0, 0, At, B0); PG8_BAR; PG8_SCHED;
;             PG8_LDB(B1, 0, 1); PG8_STAGE(PG8_SB(0, 0), b2, voffB);
;             PG8_BAR; PG8_WAIT_L(0); PG8_MMA(0, 1, At, B1); PG8_BAR;
;             PG8_LDA(At, 0, 1); PG8_STAGE(PG8_SA(0, 0), a2, voffA);
;             PG8_BAR; PG8_WAIT_L(0); PG8_MMA(1, 0, At, B0); PG8_BAR; PG8_SCHED;
;             PG8_STAGE(PG8_SB(0, 1), b2 + hstep, voffB);
;             PG8_WAIT_V(6); PG8_BAR; PG8_MMA(1, 1, At, B1); PG8_BAR;
.LBB0_745:
	s_add_i32 s93, s22, 2
	s_add_u32 s38, s0, 0x80
	s_addc_u32 s23, s1, 0
	s_add_i32 s62, 0, 0x10000
	v_add_u32_e32 v142, s62, v217
	ds_read_b128 v[130:133], v142
	ds_read_b128 v[134:137], v142 offset:1024
	ds_read_b128 v[138:141], v142 offset:2048
	ds_read_b128 v[142:145], v142 offset:3072
	s_cmp_eq_u32 s4, s22
	s_cselect_b32 s22, s90, s38
	s_cselect_b32 s23, s91, s23
	s_cselect_b32 s39, s31, s89
	s_cselect_b32 s38, s30, s88
	v_lshl_add_u64 v[192:193], s[0:1], 0, v[172:173]
	s_add_i32 m0, s80, 0xc000
	ds_read_b128 v[146:149], v218
	ds_read_b128 v[150:153], v218 offset:1024
	ds_read_b128 v[154:157], v218 offset:2048
	ds_read_b128 v[158:161], v218 offset:3072
	ds_read_b128 v[176:179], v218 offset:4096
	ds_read_b128 v[180:183], v218 offset:5120
	ds_read_b128 v[184:187], v218 offset:6144
	ds_read_b128 v[188:191], v218 offset:7168
	global_load_lds_dwordx4 v[192:193], off
	v_lshl_add_u64 v[192:193], s[0:1], 0, v[174:175]
	s_add_i32 m0, s80, 0xe000
	s_nop 0
	global_load_lds_dwordx4 v[192:193], off
	s_waitcnt lgkmcnt(8)
	s_barrier
	s_waitcnt lgkmcnt(0)
	s_setprio 1
	s_waitcnt lgkmcnt(0)
	v_mfma_f32_16x16x32_bf16 v[126:129], v[130:133], v[146:149], v[126:129]
	v_mfma_f32_16x16x32_bf16 v[122:125], v[138:141], v[146:149], v[122:125]
	v_mfma_f32_16x16x32_bf16 v[118:121], v[130:133], v[154:157], v[118:121]
	v_mfma_f32_16x16x32_bf16 v[114:117], v[138:141], v[154:157], v[114:117]
	v_mfma_f32_16x16x32_bf16 v[102:105], v[130:133], v[176:179], v[102:105]
	v_mfma_f32_16x16x32_bf16 v[98:101], v[138:141], v[176:179], v[98:101]
	v_mfma_f32_16x16x32_bf16 v[86:89], v[130:133], v[184:187], v[86:89]
	v_mfma_f32_16x16x32_bf16 v[82:85], v[138:141], v[184:187], v[82:85]
	v_mfma_f32_16x16x32_bf16 v[126:129], v[134:137], v[150:153], v[126:129]
	v_mfma_f32_16x16x32_bf16 v[122:125], v[142:145], v[150:153], v[122:125]
	v_mfma_f32_16x16x32_bf16 v[118:121], v[134:137], v[158:161], v[118:121]
	v_mfma_f32_16x16x32_bf16 v[114:117], v[142:145], v[158:161], v[114:117]
	v_mfma_f32_16x16x32_bf16 v[102:105], v[134:137], v[180:183], v[102:105]
	v_mfma_f32_16x16x32_bf16 v[98:101], v[142:145], v[180:183], v[98:101]
	v_mfma_f32_16x16x32_bf16 v[86:89], v[134:137], v[188:191], v[86:89]
	v_mfma_f32_16x16x32_bf16 v[82:85], v[142:145], v[188:191], v[82:85]
	s_setprio 0
	s_barrier
	s_add_i32 s63, 0, 0x14000
	s_add_i32 s62, s62, s79
	v_add_u32_e32 v204, s63, v217
	v_lshl_add_u64 v[208:209], s[38:39], 0, v[164:165]
	s_mov_b32 m0, s62
	ds_read_b128 v[192:195], v204
	ds_read_b128 v[196:199], v204 offset:1024
	ds_read_b128 v[200:203], v204 offset:2048
	ds_read_b128 v[204:207], v204 offset:3072
	global_load_lds_dwordx4 v[208:209], off
	v_lshl_add_u64 v[220:221], s[38:39], 0, v[170:171]
	s_add_i32 m0, s62, 0x2000
	s_nop 0
	global_load_lds_dwordx4 v[220:221], off
	s_barrier
	s_waitcnt lgkmcnt(0)
	s_setprio 1
	s_waitcnt lgkmcnt(0)
	v_mfma_f32_16x16x32_bf16 v[110:113], v[192:195], v[146:149], v[110:113]
	v_mfma_f32_16x16x32_bf16 v[106:109], v[200:203], v[146:149], v[106:109]
	v_mfma_f32_16x16x32_bf16 v[94:97], v[192:195], v[154:157], v[94:97]
	v_mfma_f32_16x16x32_bf16 v[90:93], v[200:203], v[154:157], v[90:93]
	v_mfma_f32_16x16x32_bf16 v[78:81], v[192:195], v[176:179], v[78:81]
	v_mfma_f32_16x16x32_bf16 v[74:77], v[200:203], v[176:179], v[74:77]
	v_mfma_f32_16x16x32_bf16 v[70:73], v[192:195], v[184:187], v[70:73]
	v_mfma_f32_16x16x32_bf16 v[66:69], v[200:203], v[184:187], v[66:69]
	v_mfma_f32_16x16x32_bf16 v[110:113], v[196:199], v[150:153], v[110:113]
	v_mfma_f32_16x16x32_bf16 v[106:109], v[204:207], v[150:153], v[106:109]
	v_mfma_f32_16x16x32_bf16 v[94:97], v[196:199], v[158:161], v[94:97]
	v_mfma_f32_16x16x32_bf16 v[90:93], v[204:207], v[158:161], v[90:93]
	v_mfma_f32_16x16x32_bf16 v[78:81], v[196:199], v[180:183], v[78:81]
	v_mfma_f32_16x16x32_bf16 v[74:77], v[204:207], v[180:183], v[74:77]
	v_mfma_f32_16x16x32_bf16 v[70:73], v[196:199], v[188:191], v[70:73]
	v_mfma_f32_16x16x32_bf16 v[66:69], v[204:207], v[188:191], v[66:69]
	s_setprio 0
	s_mov_b32 m0, s80
	v_lshl_add_u64 v[222:223], s[22:23], 0, v[162:163]
	s_barrier
	ds_read_b128 v[146:149], v218 offset:16384
	ds_read_b128 v[150:153], v218 offset:17408
	ds_read_b128 v[154:157], v218 offset:18432
	ds_read_b128 v[158:161], v218 offset:19456
	ds_read_b128 v[176:179], v218 offset:20480
	ds_read_b128 v[180:183], v218 offset:21504
	ds_read_b128 v[184:187], v218 offset:22528
	ds_read_b128 v[188:191], v218 offset:23552
	global_load_lds_dwordx4 v[222:223], off
	v_lshl_add_u64 v[224:225], s[22:23], 0, v[166:167]
	s_mov_b32 m0, s81
	s_nop 0
	global_load_lds_dwordx4 v[224:225], off
	s_barrier
	s_waitcnt lgkmcnt(0)
	s_setprio 1
	s_waitcnt lgkmcnt(0)
	v_mfma_f32_16x16x32_bf16 v[62:65], v[130:133], v[146:149], v[62:65]
	v_mfma_f32_16x16x32_bf16 v[58:61], v[138:141], v[146:149], v[58:61]
	v_mfma_f32_16x16x32_bf16 v[54:57], v[130:133], v[154:157], v[54:57]
	v_mfma_f32_16x16x32_bf16 v[50:53], v[138:141], v[154:157], v[50:53]
	v_mfma_f32_16x16x32_bf16 v[38:41], v[130:133], v[176:179], v[38:41]
	v_mfma_f32_16x16x32_bf16 v[34:37], v[138:141], v[176:179], v[34:37]
	v_mfma_f32_16x16x32_bf16 v[22:25], v[130:133], v[184:187], v[22:25]
	v_mfma_f32_16x16x32_bf16 v[18:21], v[138:141], v[184:187], v[18:21]
	v_mfma_f32_16x16x32_bf16 v[62:65], v[134:137], v[150:153], v[62:65]
	v_mfma_f32_16x16x32_bf16 v[58:61], v[142:145], v[150:153], v[58:61]
	v_mfma_f32_16x16x32_bf16 v[54:57], v[134:137], v[158:161], v[54:57]
	v_mfma_f32_16x16x32_bf16 v[50:53], v[142:145], v[158:161], v[50:53]
	v_mfma_f32_16x16x32_bf16 v[38:41], v[134:137], v[180:183], v[38:41]
	v_mfma_f32_16x16x32_bf16 v[34:37], v[142:145], v[180:183], v[34:37]
	v_mfma_f32_16x16x32_bf16 v[22:25], v[134:137], v[188:191], v[22:25]
	v_mfma_f32_16x16x32_bf16 v[18:21], v[142:145], v[188:191], v[18:21]
	s_setprio 0
	s_barrier
; #define PG8_STAGE(bufoff, gbase, voff) do { _Pragma("unroll") for (int _i = 0; _i < 2; ++_i) \
;         __builtin_amdgcn_global_load_lds((const unsigned*)((const char*)(gbase) + (voff)[_i]), (PG8_LAS unsigned*)(lds + (bufoff) + ldsw + _i * 8192), 16, 0, 0); } while (0)
; #define PG8_LDA(dst, b, h) do { _Pragma("unroll") for (int m = 0; m < 4; ++m) _Pragma("unroll") for (int k = 0; k < 2; ++k) dst[m][k] = *(const PG8_LAS bf16x8*)(lds + PG8_SA(b, h) + aoff + m * 2048 + k * 1024); } while (0)
; #define PG8_LDB(dst, b, h) do { _Pragma("unroll") for (int n = 0; n < 2; ++n) _Pragma("unroll") for (int k = 0; k < 2; ++k) dst[n][k] = *(const PG8_LAS bf16x8*)(lds + PG8_SB(b, h) + boff + n * 2048 + k * 1024); } while (0)
; #define PG8_MMA(ai, bj, At, Bt) do { __builtin_amdgcn_s_setprio(1); _Pragma("unroll") for (int m = 0; m < 4; ++m) _Pragma("unroll") for (int n = 0; n < 2; ++n) _Pragma("unroll") for (int k = 0; k < 2; ++k) \
;         acc[ai][bj][m][n] = __builtin_amdgcn_mfma_f32_16x16x32_bf16(Bt[n][k], At[m][k], acc[ai][bj][m][n], 0, 0, 0); __builtin_amdgcn_s_setprio(0); } while (0)
; #define PG8_WAIT_V(n) asm volatile("s_waitcnt vmcnt(" #n ")" ::: "memory")
; #define PG8_WAIT_L(n) asm volatile("s_waitcnt lgkmcnt(" #n ")" ::: "memory")
; #define PG8_BAR __builtin_amdgcn_s_barrier()
; #define PG8_SCHED __builtin_amdgcn_sched_barrier(0)
; template <class Epi, class Sched, bool STAMP = false>
; __device__ __forceinline__ void gemm_phase(PG8_LAS unsigned char* lds, const Gemm g, const Sched& S, const Epi& E, unsigned long long* stamps) {
;     ...
;             PG8_STAGE(PG8_SB(0, 1), b2 + hstep, voffB);
;             PG8_WAIT_V(6); PG8_BAR; PG8_MMA(1, 1, At, B1); PG8_BAR;
;             PG8_LDB(B0, 1, 0); PG8_SCHED; PG8_LDA(At, 1, 0); PG8_STAGE(PG8_SA(0, 1), a2 + hstep, voffA);
;             PG8_WAIT_L(8); PG8_BAR; PG8_WAIT_L(0); PG8_MMA(0, 0, At, B0); PG8_BAR; PG8_SCHED;
;             PG8_LDB(B1, 1, 1); PG8_STAGE(PG8_SB(1, 0), b3, voffB);
;             PG8_BAR; PG8_WAIT_L(0); PG8_MMA(0, 1, At, B1); PG8_BAR;
;             PG8_LDA(At, 1, 1); PG8_STAGE(PG8_SA(1, 0), a3, voffA);
;             PG8_BAR; PG8_WAIT_L(0); PG8_MMA(1, 0, At, B0); PG8_BAR; PG8_SCHED;
;             PG8_STAGE(PG8_SB(1, 1), b3 + hstep, voffB);
;             PG8_WAIT_V(6); PG8_BAR; PG8_MMA(1, 1, At, B1); PG8_BAR;
	s_add_u32 s38, s38, s94
	s_addc_u32 s39, s39, 0
	s_add_i32 s62, s63, s79
	v_lshl_add_u64 v[226:227], s[38:39], 0, v[164:165]
	s_mov_b32 m0, s62
	v_lshl_add_u64 v[228:229], s[38:39], 0, v[170:171]
	global_load_lds_dwordx4 v[226:227], off
	s_add_i32 m0, s62, 0x2000
	s_nop 0
	global_load_lds_dwordx4 v[228:229], off
	s_waitcnt vmcnt(6)
	s_barrier
	s_setprio 1
	v_mfma_f32_16x16x32_bf16 v[46:49], v[192:195], v[146:149], v[46:49]
	v_mfma_f32_16x16x32_bf16 v[42:45], v[200:203], v[146:149], v[42:45]
	v_mfma_f32_16x16x32_bf16 v[30:33], v[192:195], v[154:157], v[30:33]
	v_mfma_f32_16x16x32_bf16 v[26:29], v[200:203], v[154:157], v[26:29]
	v_mfma_f32_16x16x32_bf16 v[14:17], v[192:195], v[176:179], v[14:17]
	v_mfma_f32_16x16x32_bf16 v[10:13], v[200:203], v[176:179], v[10:13]
	v_mfma_f32_16x16x32_bf16 v[6:9], v[192:195], v[184:187], v[6:9]
	v_mfma_f32_16x16x32_bf16 v[2:5], v[200:203], v[184:187], v[2:5]
	v_mfma_f32_16x16x32_bf16 v[46:49], v[196:199], v[150:153], v[46:49]
	v_mfma_f32_16x16x32_bf16 v[42:45], v[204:207], v[150:153], v[42:45]
	v_mfma_f32_16x16x32_bf16 v[30:33], v[196:199], v[158:161], v[30:33]
	v_mfma_f32_16x16x32_bf16 v[26:29], v[204:207], v[158:161], v[26:29]
	v_mfma_f32_16x16x32_bf16 v[14:17], v[196:199], v[180:183], v[14:17]
	v_mfma_f32_16x16x32_bf16 v[10:13], v[204:207], v[180:183], v[10:13]
	v_mfma_f32_16x16x32_bf16 v[6:9], v[196:199], v[188:191], v[6:9]
	v_mfma_f32_16x16x32_bf16 v[2:5], v[204:207], v[188:191], v[2:5]
	s_setprio 0
	s_add_i32 s38, 0, 0x18000
	v_add_u32_e32 v142, s38, v217
	s_barrier
	ds_read_b128 v[130:133], v142
	ds_read_b128 v[134:137], v142 offset:1024
	ds_read_b128 v[138:141], v142 offset:2048
	ds_read_b128 v[142:145], v142 offset:3072
	s_add_u32 s22, s22, s94
	s_addc_u32 s23, s23, 0
	s_mov_b32 m0, s84
	v_lshl_add_u64 v[192:193], s[22:23], 0, v[162:163]
	ds_read_b128 v[146:149], v218 offset:32768
	ds_read_b128 v[150:153], v218 offset:33792
	ds_read_b128 v[154:157], v218 offset:34816
	ds_read_b128 v[158:161], v218 offset:35840
	ds_read_b128 v[176:179], v218 offset:36864
	ds_read_b128 v[180:183], v218 offset:37888
	ds_read_b128 v[184:187], v218 offset:38912
	ds_read_b128 v[188:191], v218 offset:39936
	global_load_lds_dwordx4 v[192:193], off
	v_lshl_add_u64 v[192:193], s[22:23], 0, v[166:167]
	s_mov_b32 m0, s85
	s_nop 0
	global_load_lds_dwordx4 v[192:193], off
	s_waitcnt lgkmcnt(8)
	s_barrier
	s_waitcnt lgkmcnt(0)
	s_setprio 1
	s_waitcnt lgkmcnt(0)
	v_mfma_f32_16x16x32_bf16 v[126:129], v[130:133], v[146:149], v[126:129]
	v_mfma_f32_16x16x32_bf16 v[122:125], v[138:141], v[146:149], v[122:125]
	v_mfma_f32_16x16x32_bf16 v[118:121], v[130:133], v[154:157], v[118:121]
	v_mfma_f32_16x16x32_bf16 v[114:117], v[138:141], v[154:157], v[114:117]
	v_mfma_f32_16x16x32_bf16 v[102:105], v[130:133], v[176:179], v[102:105]
	v_mfma_f32_16x16x32_bf16 v[98:101], v[138:141], v[176:179], v[98:101]
	v_mfma_f32_16x16x32_bf16 v[86:89], v[130:133], v[184:187], v[86:89]
	v_mfma_f32_16x16x32_bf16 v[82:85], v[138:141], v[184:187], v[82:85]
	v_mfma_f32_16x16x32_bf16 v[126:129], v[134:137], v[150:153], v[126:129]
	v_mfma_f32_16x16x32_bf16 v[122:125], v[142:145], v[150:153], v[122:125]
	v_mfma_f32_16x16x32_bf16 v[118:121], v[134:137], v[158:161], v[118:121]
	v_mfma_f32_16x16x32_bf16 v[114:117], v[142:145], v[158:161], v[114:117]
	v_mfma_f32_16x16x32_bf16 v[102:105], v[134:137], v[180:183], v[102:105]
	v_mfma_f32_16x16x32_bf16 v[98:101], v[142:145], v[180:183], v[98:101]
	v_mfma_f32_16x16x32_bf16 v[86:89], v[134:137], v[188:191], v[86:89]
	v_mfma_f32_16x16x32_bf16 v[82:85], v[142:145], v[188:191], v[82:85]
	s_setprio 0
	s_barrier
	s_add_i32 s22, s38, s79
	v_add_u32_e32 v204, s35, v217
	v_lshl_add_u64 v[208:209], v[208:209], 0, s[10:11]
	s_mov_b32 m0, s22
	ds_read_b128 v[192:195], v204
	ds_read_b128 v[196:199], v204 offset:1024
	ds_read_b128 v[200:203], v204 offset:2048
	ds_read_b128 v[204:207], v204 offset:3072
	global_load_lds_dwordx4 v[208:209], off
	v_lshl_add_u64 v[208:209], v[220:221], 0, s[10:11]
	s_add_i32 m0, s22, 0x2000
	s_nop 0
	global_load_lds_dwordx4 v[208:209], off
	s_barrier
	s_waitcnt lgkmcnt(0)
	s_setprio 1
	s_waitcnt lgkmcnt(0)
	v_mfma_f32_16x16x32_bf16 v[110:113], v[192:195], v[146:149], v[110:113]
	v_mfma_f32_16x16x32_bf16 v[106:109], v[200:203], v[146:149], v[106:109]
	v_mfma_f32_16x16x32_bf16 v[94:97], v[192:195], v[154:157], v[94:97]
	v_mfma_f32_16x16x32_bf16 v[90:93], v[200:203], v[154:157], v[90:93]
	v_mfma_f32_16x16x32_bf16 v[78:81], v[192:195], v[176:179], v[78:81]
	v_mfma_f32_16x16x32_bf16 v[74:77], v[200:203], v[176:179], v[74:77]
	v_mfma_f32_16x16x32_bf16 v[70:73], v[192:195], v[184:187], v[70:73]
	v_mfma_f32_16x16x32_bf16 v[66:69], v[200:203], v[184:187], v[66:69]
	v_mfma_f32_16x16x32_bf16 v[110:113], v[196:199], v[150:153], v[110:113]
	v_mfma_f32_16x16x32_bf16 v[106:109], v[204:207], v[150:153], v[106:109]
	v_mfma_f32_16x16x32_bf16 v[94:97], v[196:199], v[158:161], v[94:97]
	v_mfma_f32_16x16x32_bf16 v[90:93], v[204:207], v[158:161], v[90:93]
	v_mfma_f32_16x16x32_bf16 v[78:81], v[196:199], v[180:183], v[78:81]
	v_mfma_f32_16x16x32_bf16 v[74:77], v[204:207], v[180:183], v[74:77]
	v_mfma_f32_16x16x32_bf16 v[70:73], v[196:199], v[188:191], v[70:73]
	v_mfma_f32_16x16x32_bf16 v[66:69], v[204:207], v[188:191], v[66:69]
	s_setprio 0
	s_mov_b32 m0, s33
	v_lshl_add_u64 v[208:209], v[222:223], 0, s[10:11]
	s_barrier
	ds_read_b128 v[146:149], v218 offset:49152
	ds_read_b128 v[150:153], v218 offset:50176
	ds_read_b128 v[154:157], v218 offset:51200
	ds_read_b128 v[158:161], v218 offset:52224
	ds_read_b128 v[176:179], v218 offset:53248
	ds_read_b128 v[180:183], v218 offset:54272
	ds_read_b128 v[184:187], v218 offset:55296
	ds_read_b128 v[188:191], v218 offset:56320
	global_load_lds_dwordx4 v[208:209], off
	v_lshl_add_u64 v[208:209], v[224:225], 0, s[10:11]
	s_mov_b32 m0, s28
	s_nop 0
	global_load_lds_dwordx4 v[208:209], off
	s_barrier
; DI float lo2f(unsigned u) { return __uint_as_float(u << 16); }
; DI float hi2f(unsigned u) { return __uint_as_float(u & 0xffff0000u); }
; #define PG8_STAGE(bufoff, gbase, voff) do { _Pragma("unroll") for (int _i = 0; _i < 2; ++_i) \
;         __builtin_amdgcn_global_load_lds((const unsigned*)((const char*)(gbase) + (voff)[_i]), (PG8_LAS unsigned*)(lds + (bufoff) + ldsw + _i * 8192), 16, 0, 0); } while (0)
; #define PG8_WAIT_V(n) asm volatile("s_waitcnt vmcnt(" #n ")" ::: "memory")
; #define PG8_BAR __builtin_amdgcn_s_barrier()
; template <class Epi, class Sched, bool STAMP = false>
; __device__ __forceinline__ void gemm_phase(PG8_LAS unsigned char* lds, const Gemm g, const Sched& S, const Epi& E, unsigned long long* stamps) {
;     ...
;             PG8_STAGE(PG8_SB(1, 1), b3 + hstep, voffB);
;             PG8_WAIT_V(6); PG8_BAR; PG8_MMA(1, 1, At, B1); PG8_BAR;
;         }
;         if constexpr (!Epi::AFTER_DRAIN) { E(acc, cur, wr, wc, fr, fq); S.done(cur); }
;   DI void operator()(const f32x4 (&acc)[2][2][4][2], const pg8::Unit& u, int wr, int wc, int fr, int fq) const {
;     ...
; #pragma unroll
;       for (int ai = 0; ai < 2; ++ai) {
;         uint4 gs[4][2];
; #pragma unroll
;         for (int m = 0; m < 4; ++m)
; #pragma unroll
;           for (int bj = 0; bj < 2; ++bj)
;             gs[m][bj] = *(const uint4*)(o0 + (size_t)(row0 + ai * 128 + m * 16) * DFF + col0 + bj * 128);
;         __builtin_amdgcn_sched_barrier(0);
; #pragma unroll
;         for (int m = 0; m < 4; ++m)
; #pragma unroll
;           for (int bj = 0; bj < 2; ++bj) {
;             const f32x4 v0 = acc[ai][bj][m][0], v1 = acc[ai][bj][m][1];
;             const uint4 g = gs[m][bj];
;             f32x4 q0 = {lo2f(g.x) * v0[0], hi2f(g.x) * v0[1], lo2f(g.y) * v0[2], hi2f(g.y) * v0[3]};
;             f32x4 q1 = {lo2f(g.z) * v1[0], hi2f(g.z) * v1[1], lo2f(g.w) * v1[2], hi2f(g.w) * v1[3]};
;             st8(o0 + (size_t)(row0 + ai * 128 + m * 16) * DFF + col0 + bj * 128, q0, q1);
;           }
;         __builtin_amdgcn_sched_barrier(0);
;       }
; DI void conv_phase(const Params& p, int l) {
;     ...
;     float w0[8], w1[8], w2[8], bb[8];
;     load8f(cw + c0, w0); load8f(cw + DFF + c0, w1); load8f(cw + 2 * DFF + c0, w2); load8f(cb + c0, bb);
;     float prev[8], cur[8], nxt[8];
;     unpack8(rows[0], prev); unpack8(rows[1], cur);
	s_waitcnt lgkmcnt(0)
	s_setprio 1
	s_waitcnt lgkmcnt(0)
	v_mfma_f32_16x16x32_bf16 v[62:65], v[130:133], v[146:149], v[62:65]
	v_mfma_f32_16x16x32_bf16 v[58:61], v[138:141], v[146:149], v[58:61]
	v_mfma_f32_16x16x32_bf16 v[54:57], v[130:133], v[154:157], v[54:57]
	v_mfma_f32_16x16x32_bf16 v[50:53], v[138:141], v[154:157], v[50:53]
	v_mfma_f32_16x16x32_bf16 v[38:41], v[130:133], v[176:179], v[38:41]
	v_mfma_f32_16x16x32_bf16 v[34:37], v[138:141], v[176:179], v[34:37]
	v_mfma_f32_16x16x32_bf16 v[22:25], v[130:133], v[184:187], v[22:25]
	v_mfma_f32_16x16x32_bf16 v[18:21], v[138:141], v[184:187], v[18:21]
	v_mfma_f32_16x16x32_bf16 v[62:65], v[134:137], v[150:153], v[62:65]
	v_mfma_f32_16x16x32_bf16 v[58:61], v[142:145], v[150:153], v[58:61]
	v_mfma_f32_16x16x32_bf16 v[54:57], v[134:137], v[158:161], v[54:57]
	v_mfma_f32_16x16x32_bf16 v[50:53], v[142:145], v[158:161], v[50:53]
	v_mfma_f32_16x16x32_bf16 v[38:41], v[134:137], v[180:183], v[38:41]
	v_mfma_f32_16x16x32_bf16 v[34:37], v[142:145], v[180:183], v[34:37]
	v_mfma_f32_16x16x32_bf16 v[22:25], v[134:137], v[188:191], v[22:25]
	v_mfma_f32_16x16x32_bf16 v[18:21], v[142:145], v[188:191], v[18:21]
	s_setprio 0
	s_barrier
	s_add_i32 s22, s35, s79
	v_lshl_add_u64 v[130:131], v[226:227], 0, s[10:11]
	s_mov_b32 m0, s22
	s_nop 0
	global_load_lds_dwordx4 v[130:131], off
	v_lshl_add_u64 v[130:131], v[228:229], 0, s[10:11]
	s_add_i32 m0, s22, 0x2000
	s_nop 0
	global_load_lds_dwordx4 v[130:131], off
	s_waitcnt vmcnt(6)
	s_barrier
	s_setprio 1
	v_mfma_f32_16x16x32_bf16 v[46:49], v[192:195], v[146:149], v[46:49]
	v_mfma_f32_16x16x32_bf16 v[42:45], v[200:203], v[146:149], v[42:45]
	v_mfma_f32_16x16x32_bf16 v[30:33], v[192:195], v[154:157], v[30:33]
	v_mfma_f32_16x16x32_bf16 v[26:29], v[200:203], v[154:157], v[26:29]
	v_mfma_f32_16x16x32_bf16 v[14:17], v[192:195], v[176:179], v[14:17]
	v_mfma_f32_16x16x32_bf16 v[10:13], v[200:203], v[176:179], v[10:13]
	v_mfma_f32_16x16x32_bf16 v[6:9], v[192:195], v[184:187], v[6:9]
	v_mfma_f32_16x16x32_bf16 v[2:5], v[200:203], v[184:187], v[2:5]
	v_mfma_f32_16x16x32_bf16 v[46:49], v[196:199], v[150:153], v[46:49]
	v_mfma_f32_16x16x32_bf16 v[42:45], v[204:207], v[150:153], v[42:45]
	v_mfma_f32_16x16x32_bf16 v[30:33], v[196:199], v[158:161], v[30:33]
	v_mfma_f32_16x16x32_bf16 v[26:29], v[204:207], v[158:161], v[26:29]
	v_mfma_f32_16x16x32_bf16 v[14:17], v[196:199], v[180:183], v[14:17]
	v_mfma_f32_16x16x32_bf16 v[10:13], v[204:207], v[180:183], v[10:13]
	v_mfma_f32_16x16x32_bf16 v[6:9], v[196:199], v[188:191], v[6:9]
	v_mfma_f32_16x16x32_bf16 v[2:5], v[204:207], v[188:191], v[2:5]
	s_setprio 0
	s_add_u32 s0, s0, 0x100
	s_addc_u32 s1, s1, 0
	s_add_u32 s88, s88, 0x100
	s_addc_u32 s89, s89, 0
	s_cmp_ge_u32 s93, s26
	s_mov_b32 s22, s93
	s_barrier
	s_cbranch_scc0 .LBB0_745
	s_lshl_b32 s22, s75, 8
	s_lshl_b32 s0, s97, 8
	s_add_i32 s22, s22, s5
	s_or_b32 s75, s0, s72
	v_or_b32_e32 v176, s22, v1
	v_or_b32_e32 v178, s75, v216
	s_cmp_lt_i32 s77, 2
	s_mov_b64 s[0:1], -1
	s_cbranch_scc1 .LBB0_752
	s_cmp_gt_i32 s77, 2
	s_cbranch_scc0 .LBB0_749
	v_ashrrev_i32_e32 v179, 31, v178
	v_lshlrev_b64 v[180:181], 1, v[178:179]
	v_lshl_add_u64 v[180:181], s[46:47], 0, v[180:181]
	v_add_co_u32_e32 v180, vcc, 0xea000000, v180
	s_nop 1
	v_addc_co_u32_e32 v181, vcc, -1, v181, vcc
	v_lshlrev_b32_e32 v182, 2, v178
	v_readlane_b32 s98, v237, 62
	v_readlane_b32 s100, v238, 0
	v_readlane_b32 s101, v238, 1
	s_mul_i32 s98, s98, 0xab
	s_bfe_u32 s98, s98, 0x6000a
	s_mul_i32 s99, s98, 0x8400
	s_add_u32 s100, s100, s99
	s_addc_u32 s101, s101, 0
	s_nop 3
	global_load_dwordx4 v[130:133], v182, s[100:101] offset:0
	global_load_dwordx4 v[134:137], v182, s[100:101] offset:16
	s_add_u32 s100, s100, 0x2c00
	s_addc_u32 s101, s101, 0
	global_load_dwordx4 v[138:141], v182, s[100:101] offset:0
	global_load_dwordx4 v[142:145], v182, s[100:101] offset:16
	s_add_u32 s100, s100, 0x2c00
	s_addc_u32 s101, s101, 0
	global_load_dwordx4 v[146:149], v182, s[100:101] offset:0
	global_load_dwordx4 v[150:153], v182, s[100:101] offset:16
	v_readlane_b32 s100, v238, 2
	v_readlane_b32 s101, v238, 3
	s_mul_i32 s99, s98, 0x2c00
	s_add_u32 s100, s100, s99
	s_addc_u32 s101, s101, 0
	s_nop 3
	global_load_dwordx4 v[154:157], v182, s[100:101] offset:0
	global_load_dwordx4 v[158:161], v182, s[100:101] offset:16
	s_mov_b32 s98, 0x1600
	s_mov_b32 s99, 0
	s_mov_b32 s100, 0x16000000
	s_mov_b32 s101, 0
	v_add_u32_e32 v183, -1, v176
	v_mad_i64_i32 v[222:223], s[0:1], v183, s14, v[180:181]
	v_lshl_add_u64 v[224:225], v[222:223], 0, s[98:99]
	v_lshl_add_u64 v[226:227], v[224:225], 0, s[98:99]
	v_lshl_add_u64 v[196:197], v[224:225], 0, s[100:101]
	global_load_dwordx4 v[184:187], v[222:223], off
	global_load_dwordx4 v[188:191], v[224:225], off
	global_load_dwordx4 v[192:195], v[226:227], off
	v_add_u32_e32 v183, 0xf, v176
	v_mad_i64_i32 v[222:223], s[0:1], v183, s14, v[180:181]
	v_lshl_add_u64 v[224:225], v[222:223], 0, s[98:99]
	v_lshl_add_u64 v[226:227], v[224:225], 0, s[98:99]
	v_lshl_add_u64 v[220:221], v[224:225], 0, s[100:101]
	global_load_dwordx4 v[198:201], v[222:223], off
	global_load_dwordx4 v[202:205], v[224:225], off
	global_load_dwordx4 v[206:209], v[226:227], off
	s_waitcnt vmcnt(3)
; DI unsigned pack2(float a, float b) { f32x2_t v = {a, b}; bf16x2_t r = __builtin_convertvector(v, bf16x2_t); return __builtin_bit_cast(unsigned, r); }
; DI float lo2f(unsigned u) { return __uint_as_float(u << 16); }
; DI float hi2f(unsigned u) { return __uint_as_float(u & 0xffff0000u); }
; DI float sigmoidf_(float x) { return __builtin_amdgcn_rcpf(1.f + __builtin_amdgcn_exp2f(-1.4426950408889634f * x)); }
;   DI void operator()(const f32x4 (&acc)[2][2][4][2], const pg8::Unit& u, int wr, int wc, int fr, int fq) const {
;     ...
; #pragma unroll
;         for (int m = 0; m < 4; ++m)
; #pragma unroll
;           for (int bj = 0; bj < 2; ++bj) {
;             const f32x4 v0 = acc[ai][bj][m][0], v1 = acc[ai][bj][m][1];
;             const uint4 g = gs[m][bj];
;             f32x4 q0 = {lo2f(g.x) * v0[0], hi2f(g.x) * v0[1], lo2f(g.y) * v0[2], hi2f(g.y) * v0[3]};
;             f32x4 q1 = {lo2f(g.z) * v1[0], hi2f(g.z) * v1[1], lo2f(g.w) * v1[2], hi2f(g.w) * v1[3]};
;             st8(o0 + (size_t)(row0 + ai * 128 + m * 16) * DFF + col0 + bj * 128, q0, q1);
;           }
; DI void conv_phase(const Params& p, int l) {
;     ...
;     for (int i = 0; i < RUN; ++i) {
;       unpack8(rows[i + 2], nxt);
;       float o[8];
; #pragma unroll
;       for (int j = 0; j < 8; ++j) { const float g = w0[j] * prev[j] + w1[j] * cur[j] + w2[j] * nxt[j] + bb[j]; o[j] = g * sigmoidf_(g); }
;       uint4 oo; oo.x = pack2(o[0], o[1]); oo.y = pack2(o[2], o[3]); oo.z = pack2(o[4], o[5]); oo.w = pack2(o[6], o[7]);
	v_and_b32_e32 v183, 0x1fff, v176
	v_cmp_eq_u32_e32 vcc, 0, v183
	v_cndmask_b32_e64 v184, v184, 0, vcc
	v_cndmask_b32_e64 v185, v185, 0, vcc
	v_cndmask_b32_e64 v186, v186, 0, vcc
	v_cndmask_b32_e64 v187, v187, 0, vcc
	v_lshlrev_b32_e32 v240, 16, v184
	v_and_b32_e32 v241, 0xffff0000, v184
	v_lshlrev_b32_e32 v242, 16, v188
	v_and_b32_e32 v243, 0xffff0000, v188
	v_lshlrev_b32_e32 v252, 16, v192
	v_and_b32_e32 v253, 0xffff0000, v192
	v_fma_f32 v254, v130, v240, v154
	v_fma_f32 v255, v131, v241, v155
	v_fma_f32 v254, v138, v242, v254
	v_fma_f32 v255, v139, v243, v255
	v_fma_f32 v254, v146, v252, v254
	v_fma_f32 v255, v147, v253, v255
	v_mul_f32_e32 v240, 0xbfb8aa3b, v254
	v_mul_f32_e32 v241, 0xbfb8aa3b, v255
	v_exp_f32_e32 v240, v240
	v_exp_f32_e32 v241, v241
	v_add_f32_e32 v240, 1.0, v240
	v_add_f32_e32 v241, 1.0, v241
	v_rcp_f32_e32 v240, v240
	v_rcp_f32_e32 v241, v241
	v_mul_f32_e32 v254, v254, v240
	v_mul_f32_e32 v255, v255, v241
	v_mul_f32_e32 v254, v254, v126
	v_mul_f32_e32 v255, v255, v127
	v_cvt_pk_bf16_f32 v244, v254, v255
	v_lshlrev_b32_e32 v240, 16, v185
	v_and_b32_e32 v241, 0xffff0000, v185
	v_lshlrev_b32_e32 v242, 16, v189
	v_and_b32_e32 v243, 0xffff0000, v189
	v_lshlrev_b32_e32 v252, 16, v193
	v_and_b32_e32 v253, 0xffff0000, v193
	v_fma_f32 v254, v132, v240, v156
	v_fma_f32 v255, v133, v241, v157
	v_fma_f32 v254, v140, v242, v254
	v_fma_f32 v255, v141, v243, v255
	v_fma_f32 v254, v148, v252, v254
	v_fma_f32 v255, v149, v253, v255
	v_mul_f32_e32 v240, 0xbfb8aa3b, v254
	v_mul_f32_e32 v241, 0xbfb8aa3b, v255
	v_exp_f32_e32 v240, v240
	v_exp_f32_e32 v241, v241
	v_add_f32_e32 v240, 1.0, v240
	v_add_f32_e32 v241, 1.0, v241
	v_rcp_f32_e32 v240, v240
	v_rcp_f32_e32 v241, v241
	v_mul_f32_e32 v254, v254, v240
	v_mul_f32_e32 v255, v255, v241
	v_mul_f32_e32 v254, v254, v128
	v_mul_f32_e32 v255, v255, v129
	v_cvt_pk_bf16_f32 v245, v254, v255
	v_lshlrev_b32_e32 v240, 16, v186
	v_and_b32_e32 v241, 0xffff0000, v186
	v_lshlrev_b32_e32 v242, 16, v190
	v_and_b32_e32 v243, 0xffff0000, v190
	v_lshlrev_b32_e32 v252, 16, v194
	v_and_b32_e32 v253, 0xffff0000, v194
	v_fma_f32 v254, v134, v240, v158
	v_fma_f32 v255, v135, v241, v159
	v_fma_f32 v254, v142, v242, v254
	v_fma_f32 v255, v143, v243, v255
	v_fma_f32 v254, v150, v252, v254
	v_fma_f32 v255, v151, v253, v255
	v_mul_f32_e32 v240, 0xbfb8aa3b, v254
	v_mul_f32_e32 v241, 0xbfb8aa3b, v255
	v_exp_f32_e32 v240, v240
	v_exp_f32_e32 v241, v241
	v_add_f32_e32 v240, 1.0, v240
	v_add_f32_e32 v241, 1.0, v241
	v_rcp_f32_e32 v240, v240
	v_rcp_f32_e32 v241, v241
	v_mul_f32_e32 v254, v254, v240
	v_mul_f32_e32 v255, v255, v241
	v_mul_f32_e32 v254, v254, v122
	v_mul_f32_e32 v255, v255, v123
	v_cvt_pk_bf16_f32 v246, v254, v255
	v_lshlrev_b32_e32 v240, 16, v187
	v_and_b32_e32 v241, 0xffff0000, v187
	v_lshlrev_b32_e32 v242, 16, v191
	v_and_b32_e32 v243, 0xffff0000, v191
	v_lshlrev_b32_e32 v252, 16, v195
	v_and_b32_e32 v253, 0xffff0000, v195
	v_fma_f32 v254, v136, v240, v160
	v_fma_f32 v255, v137, v241, v161
	v_fma_f32 v254, v144, v242, v254
	v_fma_f32 v255, v145, v243, v255
	v_fma_f32 v254, v152, v252, v254
	v_fma_f32 v255, v153, v253, v255
	v_mul_f32_e32 v240, 0xbfb8aa3b, v254
	v_mul_f32_e32 v241, 0xbfb8aa3b, v255
	v_exp_f32_e32 v240, v240
	v_exp_f32_e32 v241, v241
	v_add_f32_e32 v240, 1.0, v240
	v_add_f32_e32 v241, 1.0, v241
	v_rcp_f32_e32 v240, v240
	v_rcp_f32_e32 v241, v241
	v_mul_f32_e32 v254, v254, v240
	v_mul_f32_e32 v255, v255, v241
	v_mul_f32_e32 v254, v254, v124
	v_mul_f32_e32 v255, v255, v125
	v_cvt_pk_bf16_f32 v247, v254, v255
	global_store_dwordx4 v[196:197], v[244:247], off
	v_add_u32_e32 v183, 0x1f, v176
	v_mad_i64_i32 v[222:223], s[0:1], v183, s14, v[180:181]
	v_lshl_add_u64 v[224:225], v[222:223], 0, s[98:99]
	v_lshl_add_u64 v[226:227], v[224:225], 0, s[98:99]
	v_lshl_add_u64 v[196:197], v[224:225], 0, s[100:101]
	global_load_dwordx4 v[184:187], v[222:223], off
	global_load_dwordx4 v[188:191], v[224:225], off
	global_load_dwordx4 v[192:195], v[226:227], off
	s_waitcnt vmcnt(4)
	v_lshlrev_b32_e32 v240, 16, v198
	v_and_b32_e32 v241, 0xffff0000, v198
	v_lshlrev_b32_e32 v242, 16, v202
	v_and_b32_e32 v243, 0xffff0000, v202
	v_lshlrev_b32_e32 v252, 16, v206
	v_and_b32_e32 v253, 0xffff0000, v206
	v_fma_f32 v254, v130, v240, v154
	v_fma_f32 v255, v131, v241, v155
	v_fma_f32 v254, v138, v242, v254
	v_fma_f32 v255, v139, v243, v255
	v_fma_f32 v254, v146, v252, v254
	v_fma_f32 v255, v147, v253, v255
	v_mul_f32_e32 v240, 0xbfb8aa3b, v254
	v_mul_f32_e32 v241, 0xbfb8aa3b, v255
	v_exp_f32_e32 v240, v240
	v_exp_f32_e32 v241, v241
	v_add_f32_e32 v240, 1.0, v240
	v_add_f32_e32 v241, 1.0, v241
	v_rcp_f32_e32 v240, v240
	v_rcp_f32_e32 v241, v241
	v_mul_f32_e32 v254, v254, v240
	v_mul_f32_e32 v255, v255, v241
	v_mul_f32_e32 v254, v254, v118
	v_mul_f32_e32 v255, v255, v119
	v_cvt_pk_bf16_f32 v248, v254, v255
	v_lshlrev_b32_e32 v240, 16, v199
	v_and_b32_e32 v241, 0xffff0000, v199
	v_lshlrev_b32_e32 v242, 16, v203
	v_and_b32_e32 v243, 0xffff0000, v203
	v_lshlrev_b32_e32 v252, 16, v207
	v_and_b32_e32 v253, 0xffff0000, v207
	v_fma_f32 v254, v132, v240, v156
	v_fma_f32 v255, v133, v241, v157
	v_fma_f32 v254, v140, v242, v254
	v_fma_f32 v255, v141, v243, v255
	v_fma_f32 v254, v148, v252, v254
	v_fma_f32 v255, v149, v253, v255
	v_mul_f32_e32 v240, 0xbfb8aa3b, v254
	v_mul_f32_e32 v241, 0xbfb8aa3b, v255
	v_exp_f32_e32 v240, v240
	v_exp_f32_e32 v241, v241
	v_add_f32_e32 v240, 1.0, v240
	v_add_f32_e32 v241, 1.0, v241
	v_rcp_f32_e32 v240, v240
	v_rcp_f32_e32 v241, v241
	v_mul_f32_e32 v254, v254, v240
	v_mul_f32_e32 v255, v255, v241
	v_mul_f32_e32 v254, v254, v120
	v_mul_f32_e32 v255, v255, v121
	v_cvt_pk_bf16_f32 v249, v254, v255
; DI unsigned pack2(float a, float b) { f32x2_t v = {a, b}; bf16x2_t r = __builtin_convertvector(v, bf16x2_t); return __builtin_bit_cast(unsigned, r); }
; DI float lo2f(unsigned u) { return __uint_as_float(u << 16); }
; DI float hi2f(unsigned u) { return __uint_as_float(u & 0xffff0000u); }
; DI float sigmoidf_(float x) { return __builtin_amdgcn_rcpf(1.f + __builtin_amdgcn_exp2f(-1.4426950408889634f * x)); }
;   DI void operator()(const f32x4 (&acc)[2][2][4][2], const pg8::Unit& u, int wr, int wc, int fr, int fq) const {
;     ...
; #pragma unroll
;         for (int m = 0; m < 4; ++m)
; #pragma unroll
;           for (int bj = 0; bj < 2; ++bj) {
;             const f32x4 v0 = acc[ai][bj][m][0], v1 = acc[ai][bj][m][1];
;             const uint4 g = gs[m][bj];
;             f32x4 q0 = {lo2f(g.x) * v0[0], hi2f(g.x) * v0[1], lo2f(g.y) * v0[2], hi2f(g.y) * v0[3]};
;             f32x4 q1 = {lo2f(g.z) * v1[0], hi2f(g.z) * v1[1], lo2f(g.w) * v1[2], hi2f(g.w) * v1[3]};
;             st8(o0 + (size_t)(row0 + ai * 128 + m * 16) * DFF + col0 + bj * 128, q0, q1);
;           }
; DI void conv_phase(const Params& p, int l) {
;     ...
;     for (int i = 0; i < RUN; ++i) {
;       unpack8(rows[i + 2], nxt);
;       float o[8];
; #pragma unroll
;       for (int j = 0; j < 8; ++j) { const float g = w0[j] * prev[j] + w1[j] * cur[j] + w2[j] * nxt[j] + bb[j]; o[j] = g * sigmoidf_(g); }
;       uint4 oo; oo.x = pack2(o[0], o[1]); oo.y = pack2(o[2], o[3]); oo.z = pack2(o[4], o[5]); oo.w = pack2(o[6], o[7]);
	v_lshlrev_b32_e32 v240, 16, v200
	v_and_b32_e32 v241, 0xffff0000, v200
	v_lshlrev_b32_e32 v242, 16, v204
	v_and_b32_e32 v243, 0xffff0000, v204
	v_lshlrev_b32_e32 v252, 16, v208
	v_and_b32_e32 v253, 0xffff0000, v208
	v_fma_f32 v254, v134, v240, v158
	v_fma_f32 v255, v135, v241, v159
	v_fma_f32 v254, v142, v242, v254
	v_fma_f32 v255, v143, v243, v255
	v_fma_f32 v254, v150, v252, v254
	v_fma_f32 v255, v151, v253, v255
	v_mul_f32_e32 v240, 0xbfb8aa3b, v254
	v_mul_f32_e32 v241, 0xbfb8aa3b, v255
	v_exp_f32_e32 v240, v240
	v_exp_f32_e32 v241, v241
	v_add_f32_e32 v240, 1.0, v240
	v_add_f32_e32 v241, 1.0, v241
	v_rcp_f32_e32 v240, v240
	v_rcp_f32_e32 v241, v241
	v_mul_f32_e32 v254, v254, v240
	v_mul_f32_e32 v255, v255, v241
	v_mul_f32_e32 v254, v254, v114
	v_mul_f32_e32 v255, v255, v115
	v_cvt_pk_bf16_f32 v250, v254, v255
	v_lshlrev_b32_e32 v240, 16, v201
	v_and_b32_e32 v241, 0xffff0000, v201
	v_lshlrev_b32_e32 v242, 16, v205
	v_and_b32_e32 v243, 0xffff0000, v205
	v_lshlrev_b32_e32 v252, 16, v209
	v_and_b32_e32 v253, 0xffff0000, v209
	v_fma_f32 v254, v136, v240, v160
	v_fma_f32 v255, v137, v241, v161
	v_fma_f32 v254, v144, v242, v254
	v_fma_f32 v255, v145, v243, v255
	v_fma_f32 v254, v152, v252, v254
	v_fma_f32 v255, v153, v253, v255
	v_mul_f32_e32 v240, 0xbfb8aa3b, v254
	v_mul_f32_e32 v241, 0xbfb8aa3b, v255
	v_exp_f32_e32 v240, v240
	v_exp_f32_e32 v241, v241
	v_add_f32_e32 v240, 1.0, v240
	v_add_f32_e32 v241, 1.0, v241
	v_rcp_f32_e32 v240, v240
	v_rcp_f32_e32 v241, v241
	v_mul_f32_e32 v254, v254, v240
	v_mul_f32_e32 v255, v255, v241
	v_mul_f32_e32 v254, v254, v116
	v_mul_f32_e32 v255, v255, v117
	v_cvt_pk_bf16_f32 v251, v254, v255
	global_store_dwordx4 v[220:221], v[248:251], off
	v_add_u32_e32 v183, 0x2f, v176
	v_mad_i64_i32 v[222:223], s[0:1], v183, s14, v[180:181]
	v_lshl_add_u64 v[224:225], v[222:223], 0, s[98:99]
	v_lshl_add_u64 v[226:227], v[224:225], 0, s[98:99]
	v_lshl_add_u64 v[220:221], v[224:225], 0, s[100:101]
	global_load_dwordx4 v[198:201], v[222:223], off
	global_load_dwordx4 v[202:205], v[224:225], off
	global_load_dwordx4 v[206:209], v[226:227], off
	s_waitcnt vmcnt(4)
	v_lshlrev_b32_e32 v240, 16, v184
	v_and_b32_e32 v241, 0xffff0000, v184
	v_lshlrev_b32_e32 v242, 16, v188
	v_and_b32_e32 v243, 0xffff0000, v188
	v_lshlrev_b32_e32 v252, 16, v192
	v_and_b32_e32 v253, 0xffff0000, v192
	v_fma_f32 v254, v130, v240, v154
	v_fma_f32 v255, v131, v241, v155
	v_fma_f32 v254, v138, v242, v254
	v_fma_f32 v255, v139, v243, v255
	v_fma_f32 v254, v146, v252, v254
	v_fma_f32 v255, v147, v253, v255
	v_mul_f32_e32 v240, 0xbfb8aa3b, v254
	v_mul_f32_e32 v241, 0xbfb8aa3b, v255
	v_exp_f32_e32 v240, v240
	v_exp_f32_e32 v241, v241
	v_add_f32_e32 v240, 1.0, v240
	v_add_f32_e32 v241, 1.0, v241
	v_rcp_f32_e32 v240, v240
	v_rcp_f32_e32 v241, v241
	v_mul_f32_e32 v254, v254, v240
	v_mul_f32_e32 v255, v255, v241
	v_mul_f32_e32 v254, v254, v102
	v_mul_f32_e32 v255, v255, v103
	v_cvt_pk_bf16_f32 v244, v254, v255
	v_lshlrev_b32_e32 v240, 16, v185
	v_and_b32_e32 v241, 0xffff0000, v185
	v_lshlrev_b32_e32 v242, 16, v189
	v_and_b32_e32 v243, 0xffff0000, v189
	v_lshlrev_b32_e32 v252, 16, v193
	v_and_b32_e32 v253, 0xffff0000, v193
	v_fma_f32 v254, v132, v240, v156
	v_fma_f32 v255, v133, v241, v157
	v_fma_f32 v254, v140, v242, v254
	v_fma_f32 v255, v141, v243, v255
	v_fma_f32 v254, v148, v252, v254
	v_fma_f32 v255, v149, v253, v255
	v_mul_f32_e32 v240, 0xbfb8aa3b, v254
	v_mul_f32_e32 v241, 0xbfb8aa3b, v255
	v_exp_f32_e32 v240, v240
	v_exp_f32_e32 v241, v241
	v_add_f32_e32 v240, 1.0, v240
	v_add_f32_e32 v241, 1.0, v241
	v_rcp_f32_e32 v240, v240
	v_rcp_f32_e32 v241, v241
	v_mul_f32_e32 v254, v254, v240
	v_mul_f32_e32 v255, v255, v241
	v_mul_f32_e32 v254, v254, v104
	v_mul_f32_e32 v255, v255, v105
	v_cvt_pk_bf16_f32 v245, v254, v255
	v_lshlrev_b32_e32 v240, 16, v186
	v_and_b32_e32 v241, 0xffff0000, v186
	v_lshlrev_b32_e32 v242, 16, v190
	v_and_b32_e32 v243, 0xffff0000, v190
	v_lshlrev_b32_e32 v252, 16, v194
	v_and_b32_e32 v253, 0xffff0000, v194
	v_fma_f32 v254, v134, v240, v158
	v_fma_f32 v255, v135, v241, v159
	v_fma_f32 v254, v142, v242, v254
	v_fma_f32 v255, v143, v243, v255
	v_fma_f32 v254, v150, v252, v254
	v_fma_f32 v255, v151, v253, v255
	v_mul_f32_e32 v240, 0xbfb8aa3b, v254
	v_mul_f32_e32 v241, 0xbfb8aa3b, v255
	v_exp_f32_e32 v240, v240
	v_exp_f32_e32 v241, v241
	v_add_f32_e32 v240, 1.0, v240
	v_add_f32_e32 v241, 1.0, v241
	v_rcp_f32_e32 v240, v240
	v_rcp_f32_e32 v241, v241
	v_mul_f32_e32 v254, v254, v240
	v_mul_f32_e32 v255, v255, v241
	v_mul_f32_e32 v254, v254, v98
	v_mul_f32_e32 v255, v255, v99
	v_cvt_pk_bf16_f32 v246, v254, v255
	v_lshlrev_b32_e32 v240, 16, v187
	v_and_b32_e32 v241, 0xffff0000, v187
	v_lshlrev_b32_e32 v242, 16, v191
	v_and_b32_e32 v243, 0xffff0000, v191
	v_lshlrev_b32_e32 v252, 16, v195
	v_and_b32_e32 v253, 0xffff0000, v195
	v_fma_f32 v254, v136, v240, v160
	v_fma_f32 v255, v137, v241, v161
	v_fma_f32 v254, v144, v242, v254
	v_fma_f32 v255, v145, v243, v255
	v_fma_f32 v254, v152, v252, v254
	v_fma_f32 v255, v153, v253, v255
	v_mul_f32_e32 v240, 0xbfb8aa3b, v254
	v_mul_f32_e32 v241, 0xbfb8aa3b, v255
	v_exp_f32_e32 v240, v240
	v_exp_f32_e32 v241, v241
	v_add_f32_e32 v240, 1.0, v240
	v_add_f32_e32 v241, 1.0, v241
	v_rcp_f32_e32 v240, v240
	v_rcp_f32_e32 v241, v241
	v_mul_f32_e32 v254, v254, v240
	v_mul_f32_e32 v255, v255, v241
	v_mul_f32_e32 v254, v254, v100
	v_mul_f32_e32 v255, v255, v101
	v_cvt_pk_bf16_f32 v247, v254, v255
	global_store_dwordx4 v[196:197], v[244:247], off
	v_add_u32_e32 v183, 0x7f, v176
	v_mad_i64_i32 v[222:223], s[0:1], v183, s14, v[180:181]
	v_lshl_add_u64 v[224:225], v[222:223], 0, s[98:99]
	v_lshl_add_u64 v[226:227], v[224:225], 0, s[98:99]
	v_lshl_add_u64 v[196:197], v[224:225], 0, s[100:101]
	global_load_dwordx4 v[184:187], v[222:223], off
	global_load_dwordx4 v[188:191], v[224:225], off
	global_load_dwordx4 v[192:195], v[226:227], off
	s_waitcnt vmcnt(4)
; DI unsigned pack2(float a, float b) { f32x2_t v = {a, b}; bf16x2_t r = __builtin_convertvector(v, bf16x2_t); return __builtin_bit_cast(unsigned, r); }
; DI float lo2f(unsigned u) { return __uint_as_float(u << 16); }
; DI float hi2f(unsigned u) { return __uint_as_float(u & 0xffff0000u); }
; DI float sigmoidf_(float x) { return __builtin_amdgcn_rcpf(1.f + __builtin_amdgcn_exp2f(-1.4426950408889634f * x)); }
;   DI void operator()(const f32x4 (&acc)[2][2][4][2], const pg8::Unit& u, int wr, int wc, int fr, int fq) const {
;     ...
; #pragma unroll
;         for (int m = 0; m < 4; ++m)
; #pragma unroll
;           for (int bj = 0; bj < 2; ++bj) {
;             const f32x4 v0 = acc[ai][bj][m][0], v1 = acc[ai][bj][m][1];
;             const uint4 g = gs[m][bj];
;             f32x4 q0 = {lo2f(g.x) * v0[0], hi2f(g.x) * v0[1], lo2f(g.y) * v0[2], hi2f(g.y) * v0[3]};
;             f32x4 q1 = {lo2f(g.z) * v1[0], hi2f(g.z) * v1[1], lo2f(g.w) * v1[2], hi2f(g.w) * v1[3]};
;             st8(o0 + (size_t)(row0 + ai * 128 + m * 16) * DFF + col0 + bj * 128, q0, q1);
;           }
; DI void conv_phase(const Params& p, int l) {
;     ...
;     for (int i = 0; i < RUN; ++i) {
;       unpack8(rows[i + 2], nxt);
;       float o[8];
; #pragma unroll
;       for (int j = 0; j < 8; ++j) { const float g = w0[j] * prev[j] + w1[j] * cur[j] + w2[j] * nxt[j] + bb[j]; o[j] = g * sigmoidf_(g); }
;       uint4 oo; oo.x = pack2(o[0], o[1]); oo.y = pack2(o[2], o[3]); oo.z = pack2(o[4], o[5]); oo.w = pack2(o[6], o[7]);
	v_lshlrev_b32_e32 v240, 16, v198
	v_and_b32_e32 v241, 0xffff0000, v198
	v_lshlrev_b32_e32 v242, 16, v202
	v_and_b32_e32 v243, 0xffff0000, v202
	v_lshlrev_b32_e32 v252, 16, v206
	v_and_b32_e32 v253, 0xffff0000, v206
	v_fma_f32 v254, v130, v240, v154
	v_fma_f32 v255, v131, v241, v155
	v_fma_f32 v254, v138, v242, v254
	v_fma_f32 v255, v139, v243, v255
	v_fma_f32 v254, v146, v252, v254
	v_fma_f32 v255, v147, v253, v255
	v_mul_f32_e32 v240, 0xbfb8aa3b, v254
	v_mul_f32_e32 v241, 0xbfb8aa3b, v255
	v_exp_f32_e32 v240, v240
	v_exp_f32_e32 v241, v241
	v_add_f32_e32 v240, 1.0, v240
	v_add_f32_e32 v241, 1.0, v241
	v_rcp_f32_e32 v240, v240
	v_rcp_f32_e32 v241, v241
	v_mul_f32_e32 v254, v254, v240
	v_mul_f32_e32 v255, v255, v241
	v_mul_f32_e32 v254, v254, v86
	v_mul_f32_e32 v255, v255, v87
	v_cvt_pk_bf16_f32 v248, v254, v255
	v_lshlrev_b32_e32 v240, 16, v199
	v_and_b32_e32 v241, 0xffff0000, v199
	v_lshlrev_b32_e32 v242, 16, v203
	v_and_b32_e32 v243, 0xffff0000, v203
	v_lshlrev_b32_e32 v252, 16, v207
	v_and_b32_e32 v253, 0xffff0000, v207
	v_fma_f32 v254, v132, v240, v156
	v_fma_f32 v255, v133, v241, v157
	v_fma_f32 v254, v140, v242, v254
	v_fma_f32 v255, v141, v243, v255
	v_fma_f32 v254, v148, v252, v254
	v_fma_f32 v255, v149, v253, v255
	v_mul_f32_e32 v240, 0xbfb8aa3b, v254
	v_mul_f32_e32 v241, 0xbfb8aa3b, v255
	v_exp_f32_e32 v240, v240
	v_exp_f32_e32 v241, v241
	v_add_f32_e32 v240, 1.0, v240
	v_add_f32_e32 v241, 1.0, v241
	v_rcp_f32_e32 v240, v240
	v_rcp_f32_e32 v241, v241
	v_mul_f32_e32 v254, v254, v240
	v_mul_f32_e32 v255, v255, v241
	v_mul_f32_e32 v254, v254, v88
	v_mul_f32_e32 v255, v255, v89
	v_cvt_pk_bf16_f32 v249, v254, v255
	v_lshlrev_b32_e32 v240, 16, v200
	v_and_b32_e32 v241, 0xffff0000, v200
	v_lshlrev_b32_e32 v242, 16, v204
	v_and_b32_e32 v243, 0xffff0000, v204
	v_lshlrev_b32_e32 v252, 16, v208
	v_and_b32_e32 v253, 0xffff0000, v208
	v_fma_f32 v254, v134, v240, v158
	v_fma_f32 v255, v135, v241, v159
	v_fma_f32 v254, v142, v242, v254
	v_fma_f32 v255, v143, v243, v255
	v_fma_f32 v254, v150, v252, v254
	v_fma_f32 v255, v151, v253, v255
	v_mul_f32_e32 v240, 0xbfb8aa3b, v254
	v_mul_f32_e32 v241, 0xbfb8aa3b, v255
	v_exp_f32_e32 v240, v240
	v_exp_f32_e32 v241, v241
	v_add_f32_e32 v240, 1.0, v240
	v_add_f32_e32 v241, 1.0, v241
	v_rcp_f32_e32 v240, v240
	v_rcp_f32_e32 v241, v241
	v_mul_f32_e32 v254, v254, v240
	v_mul_f32_e32 v255, v255, v241
	v_mul_f32_e32 v254, v254, v82
	v_mul_f32_e32 v255, v255, v83
	v_cvt_pk_bf16_f32 v250, v254, v255
	v_lshlrev_b32_e32 v240, 16, v201
	v_and_b32_e32 v241, 0xffff0000, v201
	v_lshlrev_b32_e32 v242, 16, v205
	v_and_b32_e32 v243, 0xffff0000, v205
	v_lshlrev_b32_e32 v252, 16, v209
	v_and_b32_e32 v253, 0xffff0000, v209
	v_fma_f32 v254, v136, v240, v160
	v_fma_f32 v255, v137, v241, v161
	v_fma_f32 v254, v144, v242, v254
	v_fma_f32 v255, v145, v243, v255
	v_fma_f32 v254, v152, v252, v254
	v_fma_f32 v255, v153, v253, v255
	v_mul_f32_e32 v240, 0xbfb8aa3b, v254
	v_mul_f32_e32 v241, 0xbfb8aa3b, v255
	v_exp_f32_e32 v240, v240
	v_exp_f32_e32 v241, v241
	v_add_f32_e32 v240, 1.0, v240
	v_add_f32_e32 v241, 1.0, v241
	v_rcp_f32_e32 v240, v240
	v_rcp_f32_e32 v241, v241
	v_mul_f32_e32 v254, v254, v240
	v_mul_f32_e32 v255, v255, v241
	v_mul_f32_e32 v254, v254, v84
	v_mul_f32_e32 v255, v255, v85
	v_cvt_pk_bf16_f32 v251, v254, v255
	global_store_dwordx4 v[220:221], v[248:251], off
	v_add_u32_e32 v183, 0x8f, v176
	v_mad_i64_i32 v[222:223], s[0:1], v183, s14, v[180:181]
	v_lshl_add_u64 v[224:225], v[222:223], 0, s[98:99]
	v_lshl_add_u64 v[226:227], v[224:225], 0, s[98:99]
	v_lshl_add_u64 v[220:221], v[224:225], 0, s[100:101]
	global_load_dwordx4 v[198:201], v[222:223], off
	global_load_dwordx4 v[202:205], v[224:225], off
	global_load_dwordx4 v[206:209], v[226:227], off
	s_waitcnt vmcnt(4)
	v_lshlrev_b32_e32 v240, 16, v184
	v_and_b32_e32 v241, 0xffff0000, v184
	v_lshlrev_b32_e32 v242, 16, v188
	v_and_b32_e32 v243, 0xffff0000, v188
	v_lshlrev_b32_e32 v252, 16, v192
	v_and_b32_e32 v253, 0xffff0000, v192
	v_fma_f32 v254, v130, v240, v154
	v_fma_f32 v255, v131, v241, v155
	v_fma_f32 v254, v138, v242, v254
	v_fma_f32 v255, v139, v243, v255
	v_fma_f32 v254, v146, v252, v254
	v_fma_f32 v255, v147, v253, v255
	v_mul_f32_e32 v240, 0xbfb8aa3b, v254
	v_mul_f32_e32 v241, 0xbfb8aa3b, v255
	v_exp_f32_e32 v240, v240
	v_exp_f32_e32 v241, v241
	v_add_f32_e32 v240, 1.0, v240
	v_add_f32_e32 v241, 1.0, v241
	v_rcp_f32_e32 v240, v240
	v_rcp_f32_e32 v241, v241
	v_mul_f32_e32 v254, v254, v240
	v_mul_f32_e32 v255, v255, v241
	v_mul_f32_e32 v254, v254, v62
	v_mul_f32_e32 v255, v255, v63
	v_cvt_pk_bf16_f32 v244, v254, v255
	v_lshlrev_b32_e32 v240, 16, v185
	v_and_b32_e32 v241, 0xffff0000, v185
	v_lshlrev_b32_e32 v242, 16, v189
	v_and_b32_e32 v243, 0xffff0000, v189
	v_lshlrev_b32_e32 v252, 16, v193
	v_and_b32_e32 v253, 0xffff0000, v193
	v_fma_f32 v254, v132, v240, v156
	v_fma_f32 v255, v133, v241, v157
	v_fma_f32 v254, v140, v242, v254
	v_fma_f32 v255, v141, v243, v255
	v_fma_f32 v254, v148, v252, v254
	v_fma_f32 v255, v149, v253, v255
	v_mul_f32_e32 v240, 0xbfb8aa3b, v254
	v_mul_f32_e32 v241, 0xbfb8aa3b, v255
	v_exp_f32_e32 v240, v240
	v_exp_f32_e32 v241, v241
	v_add_f32_e32 v240, 1.0, v240
	v_add_f32_e32 v241, 1.0, v241
	v_rcp_f32_e32 v240, v240
	v_rcp_f32_e32 v241, v241
	v_mul_f32_e32 v254, v254, v240
	v_mul_f32_e32 v255, v255, v241
	v_mul_f32_e32 v254, v254, v64
	v_mul_f32_e32 v255, v255, v65
	v_cvt_pk_bf16_f32 v245, v254, v255
	v_lshlrev_b32_e32 v240, 16, v186
	v_and_b32_e32 v241, 0xffff0000, v186
	v_lshlrev_b32_e32 v242, 16, v190
	v_and_b32_e32 v243, 0xffff0000, v190
	v_lshlrev_b32_e32 v252, 16, v194
	v_and_b32_e32 v253, 0xffff0000, v194
; DI unsigned pack2(float a, float b) { f32x2_t v = {a, b}; bf16x2_t r = __builtin_convertvector(v, bf16x2_t); return __builtin_bit_cast(unsigned, r); }
; DI float lo2f(unsigned u) { return __uint_as_float(u << 16); }
; DI float hi2f(unsigned u) { return __uint_as_float(u & 0xffff0000u); }
; DI float sigmoidf_(float x) { return __builtin_amdgcn_rcpf(1.f + __builtin_amdgcn_exp2f(-1.4426950408889634f * x)); }
;   DI void operator()(const f32x4 (&acc)[2][2][4][2], const pg8::Unit& u, int wr, int wc, int fr, int fq) const {
;     ...
; #pragma unroll
;         for (int m = 0; m < 4; ++m)
; #pragma unroll
;           for (int bj = 0; bj < 2; ++bj) {
;             const f32x4 v0 = acc[ai][bj][m][0], v1 = acc[ai][bj][m][1];
;             const uint4 g = gs[m][bj];
;             f32x4 q0 = {lo2f(g.x) * v0[0], hi2f(g.x) * v0[1], lo2f(g.y) * v0[2], hi2f(g.y) * v0[3]};
;             f32x4 q1 = {lo2f(g.z) * v1[0], hi2f(g.z) * v1[1], lo2f(g.w) * v1[2], hi2f(g.w) * v1[3]};
;             st8(o0 + (size_t)(row0 + ai * 128 + m * 16) * DFF + col0 + bj * 128, q0, q1);
;           }
; DI void conv_phase(const Params& p, int l) {
;     ...
;     for (int i = 0; i < RUN; ++i) {
;       unpack8(rows[i + 2], nxt);
;       float o[8];
; #pragma unroll
;       for (int j = 0; j < 8; ++j) { const float g = w0[j] * prev[j] + w1[j] * cur[j] + w2[j] * nxt[j] + bb[j]; o[j] = g * sigmoidf_(g); }
;       uint4 oo; oo.x = pack2(o[0], o[1]); oo.y = pack2(o[2], o[3]); oo.z = pack2(o[4], o[5]); oo.w = pack2(o[6], o[7]);
	v_fma_f32 v254, v134, v240, v158
	v_fma_f32 v255, v135, v241, v159
	v_fma_f32 v254, v142, v242, v254
	v_fma_f32 v255, v143, v243, v255
	v_fma_f32 v254, v150, v252, v254
	v_fma_f32 v255, v151, v253, v255
	v_mul_f32_e32 v240, 0xbfb8aa3b, v254
	v_mul_f32_e32 v241, 0xbfb8aa3b, v255
	v_exp_f32_e32 v240, v240
	v_exp_f32_e32 v241, v241
	v_add_f32_e32 v240, 1.0, v240
	v_add_f32_e32 v241, 1.0, v241
	v_rcp_f32_e32 v240, v240
	v_rcp_f32_e32 v241, v241
	v_mul_f32_e32 v254, v254, v240
	v_mul_f32_e32 v255, v255, v241
	v_mul_f32_e32 v254, v254, v58
	v_mul_f32_e32 v255, v255, v59
	v_cvt_pk_bf16_f32 v246, v254, v255
	v_lshlrev_b32_e32 v240, 16, v187
	v_and_b32_e32 v241, 0xffff0000, v187
	v_lshlrev_b32_e32 v242, 16, v191
	v_and_b32_e32 v243, 0xffff0000, v191
	v_lshlrev_b32_e32 v252, 16, v195
	v_and_b32_e32 v253, 0xffff0000, v195
	v_fma_f32 v254, v136, v240, v160
	v_fma_f32 v255, v137, v241, v161
	v_fma_f32 v254, v144, v242, v254
	v_fma_f32 v255, v145, v243, v255
	v_fma_f32 v254, v152, v252, v254
	v_fma_f32 v255, v153, v253, v255
	v_mul_f32_e32 v240, 0xbfb8aa3b, v254
	v_mul_f32_e32 v241, 0xbfb8aa3b, v255
	v_exp_f32_e32 v240, v240
	v_exp_f32_e32 v241, v241
	v_add_f32_e32 v240, 1.0, v240
	v_add_f32_e32 v241, 1.0, v241
	v_rcp_f32_e32 v240, v240
	v_rcp_f32_e32 v241, v241
	v_mul_f32_e32 v254, v254, v240
	v_mul_f32_e32 v255, v255, v241
	v_mul_f32_e32 v254, v254, v60
	v_mul_f32_e32 v255, v255, v61
	v_cvt_pk_bf16_f32 v247, v254, v255
	global_store_dwordx4 v[196:197], v[244:247], off
	v_add_u32_e32 v183, 0x9f, v176
	v_mad_i64_i32 v[222:223], s[0:1], v183, s14, v[180:181]
	v_lshl_add_u64 v[224:225], v[222:223], 0, s[98:99]
	v_lshl_add_u64 v[226:227], v[224:225], 0, s[98:99]
	v_lshl_add_u64 v[196:197], v[224:225], 0, s[100:101]
	global_load_dwordx4 v[184:187], v[222:223], off
	global_load_dwordx4 v[188:191], v[224:225], off
	global_load_dwordx4 v[192:195], v[226:227], off
	s_waitcnt vmcnt(4)
	v_lshlrev_b32_e32 v240, 16, v198
	v_and_b32_e32 v241, 0xffff0000, v198
	v_lshlrev_b32_e32 v242, 16, v202
	v_and_b32_e32 v243, 0xffff0000, v202
	v_lshlrev_b32_e32 v252, 16, v206
	v_and_b32_e32 v253, 0xffff0000, v206
	v_fma_f32 v254, v130, v240, v154
	v_fma_f32 v255, v131, v241, v155
	v_fma_f32 v254, v138, v242, v254
	v_fma_f32 v255, v139, v243, v255
	v_fma_f32 v254, v146, v252, v254
	v_fma_f32 v255, v147, v253, v255
	v_mul_f32_e32 v240, 0xbfb8aa3b, v254
	v_mul_f32_e32 v241, 0xbfb8aa3b, v255
	v_exp_f32_e32 v240, v240
	v_exp_f32_e32 v241, v241
	v_add_f32_e32 v240, 1.0, v240
	v_add_f32_e32 v241, 1.0, v241
	v_rcp_f32_e32 v240, v240
	v_rcp_f32_e32 v241, v241
	v_mul_f32_e32 v254, v254, v240
	v_mul_f32_e32 v255, v255, v241
	v_mul_f32_e32 v254, v254, v54
	v_mul_f32_e32 v255, v255, v55
	v_cvt_pk_bf16_f32 v248, v254, v255
	v_lshlrev_b32_e32 v240, 16, v199
	v_and_b32_e32 v241, 0xffff0000, v199
	v_lshlrev_b32_e32 v242, 16, v203
	v_and_b32_e32 v243, 0xffff0000, v203
	v_lshlrev_b32_e32 v252, 16, v207
	v_and_b32_e32 v253, 0xffff0000, v207
	v_fma_f32 v254, v132, v240, v156
	v_fma_f32 v255, v133, v241, v157
	v_fma_f32 v254, v140, v242, v254
	v_fma_f32 v255, v141, v243, v255
	v_fma_f32 v254, v148, v252, v254
	v_fma_f32 v255, v149, v253, v255
	v_mul_f32_e32 v240, 0xbfb8aa3b, v254
	v_mul_f32_e32 v241, 0xbfb8aa3b, v255
	v_exp_f32_e32 v240, v240
	v_exp_f32_e32 v241, v241
	v_add_f32_e32 v240, 1.0, v240
	v_add_f32_e32 v241, 1.0, v241
	v_rcp_f32_e32 v240, v240
	v_rcp_f32_e32 v241, v241
	v_mul_f32_e32 v254, v254, v240
	v_mul_f32_e32 v255, v255, v241
	v_mul_f32_e32 v254, v254, v56
	v_mul_f32_e32 v255, v255, v57
	v_cvt_pk_bf16_f32 v249, v254, v255
	v_lshlrev_b32_e32 v240, 16, v200
	v_and_b32_e32 v241, 0xffff0000, v200
	v_lshlrev_b32_e32 v242, 16, v204
	v_and_b32_e32 v243, 0xffff0000, v204
	v_lshlrev_b32_e32 v252, 16, v208
	v_and_b32_e32 v253, 0xffff0000, v208
	v_fma_f32 v254, v134, v240, v158
	v_fma_f32 v255, v135, v241, v159
	v_fma_f32 v254, v142, v242, v254
	v_fma_f32 v255, v143, v243, v255
	v_fma_f32 v254, v150, v252, v254
	v_fma_f32 v255, v151, v253, v255
	v_mul_f32_e32 v240, 0xbfb8aa3b, v254
	v_mul_f32_e32 v241, 0xbfb8aa3b, v255
	v_exp_f32_e32 v240, v240
	v_exp_f32_e32 v241, v241
	v_add_f32_e32 v240, 1.0, v240
	v_add_f32_e32 v241, 1.0, v241
	v_rcp_f32_e32 v240, v240
	v_rcp_f32_e32 v241, v241
	v_mul_f32_e32 v254, v254, v240
	v_mul_f32_e32 v255, v255, v241
	v_mul_f32_e32 v254, v254, v50
	v_mul_f32_e32 v255, v255, v51
	v_cvt_pk_bf16_f32 v250, v254, v255
	v_lshlrev_b32_e32 v240, 16, v201
	v_and_b32_e32 v241, 0xffff0000, v201
	v_lshlrev_b32_e32 v242, 16, v205
	v_and_b32_e32 v243, 0xffff0000, v205
	v_lshlrev_b32_e32 v252, 16, v209
	v_and_b32_e32 v253, 0xffff0000, v209
	v_fma_f32 v254, v136, v240, v160
	v_fma_f32 v255, v137, v241, v161
	v_fma_f32 v254, v144, v242, v254
	v_fma_f32 v255, v145, v243, v255
	v_fma_f32 v254, v152, v252, v254
	v_fma_f32 v255, v153, v253, v255
	v_mul_f32_e32 v240, 0xbfb8aa3b, v254
	v_mul_f32_e32 v241, 0xbfb8aa3b, v255
	v_exp_f32_e32 v240, v240
	v_exp_f32_e32 v241, v241
	v_add_f32_e32 v240, 1.0, v240
	v_add_f32_e32 v241, 1.0, v241
	v_rcp_f32_e32 v240, v240
	v_rcp_f32_e32 v241, v241
	v_mul_f32_e32 v254, v254, v240
	v_mul_f32_e32 v255, v255, v241
	v_mul_f32_e32 v254, v254, v52
	v_mul_f32_e32 v255, v255, v53
	v_cvt_pk_bf16_f32 v251, v254, v255
	global_store_dwordx4 v[220:221], v[248:251], off
	v_add_u32_e32 v183, 0xaf, v176
	v_mad_i64_i32 v[222:223], s[0:1], v183, s14, v[180:181]
	v_lshl_add_u64 v[224:225], v[222:223], 0, s[98:99]
	v_lshl_add_u64 v[226:227], v[224:225], 0, s[98:99]
	v_lshl_add_u64 v[220:221], v[224:225], 0, s[100:101]
	global_load_dwordx4 v[198:201], v[222:223], off
	global_load_dwordx4 v[202:205], v[224:225], off
	global_load_dwordx4 v[206:209], v[226:227], off
	s_waitcnt vmcnt(4)
; DI unsigned pack2(float a, float b) { f32x2_t v = {a, b}; bf16x2_t r = __builtin_convertvector(v, bf16x2_t); return __builtin_bit_cast(unsigned, r); }
; DI float lo2f(unsigned u) { return __uint_as_float(u << 16); }
; DI float hi2f(unsigned u) { return __uint_as_float(u & 0xffff0000u); }
; DI float sigmoidf_(float x) { return __builtin_amdgcn_rcpf(1.f + __builtin_amdgcn_exp2f(-1.4426950408889634f * x)); }
;   DI void operator()(const f32x4 (&acc)[2][2][4][2], const pg8::Unit& u, int wr, int wc, int fr, int fq) const {
;     ...
; #pragma unroll
;         for (int m = 0; m < 4; ++m)
; #pragma unroll
;           for (int bj = 0; bj < 2; ++bj) {
;             const f32x4 v0 = acc[ai][bj][m][0], v1 = acc[ai][bj][m][1];
;             const uint4 g = gs[m][bj];
;             f32x4 q0 = {lo2f(g.x) * v0[0], hi2f(g.x) * v0[1], lo2f(g.y) * v0[2], hi2f(g.y) * v0[3]};
;             f32x4 q1 = {lo2f(g.z) * v1[0], hi2f(g.z) * v1[1], lo2f(g.w) * v1[2], hi2f(g.w) * v1[3]};
;             st8(o0 + (size_t)(row0 + ai * 128 + m * 16) * DFF + col0 + bj * 128, q0, q1);
;           }
; DI void conv_phase(const Params& p, int l) {
;     ...
;     for (int i = 0; i < RUN; ++i) {
;       unpack8(rows[i + 2], nxt);
;       float o[8];
; #pragma unroll
;       for (int j = 0; j < 8; ++j) { const float g = w0[j] * prev[j] + w1[j] * cur[j] + w2[j] * nxt[j] + bb[j]; o[j] = g * sigmoidf_(g); }
;       uint4 oo; oo.x = pack2(o[0], o[1]); oo.y = pack2(o[2], o[3]); oo.z = pack2(o[4], o[5]); oo.w = pack2(o[6], o[7]);
	v_lshlrev_b32_e32 v240, 16, v184
	v_and_b32_e32 v241, 0xffff0000, v184
	v_lshlrev_b32_e32 v242, 16, v188
	v_and_b32_e32 v243, 0xffff0000, v188
	v_lshlrev_b32_e32 v252, 16, v192
	v_and_b32_e32 v253, 0xffff0000, v192
	v_fma_f32 v254, v130, v240, v154
	v_fma_f32 v255, v131, v241, v155
	v_fma_f32 v254, v138, v242, v254
	v_fma_f32 v255, v139, v243, v255
	v_fma_f32 v254, v146, v252, v254
	v_fma_f32 v255, v147, v253, v255
	v_mul_f32_e32 v240, 0xbfb8aa3b, v254
	v_mul_f32_e32 v241, 0xbfb8aa3b, v255
	v_exp_f32_e32 v240, v240
	v_exp_f32_e32 v241, v241
	v_add_f32_e32 v240, 1.0, v240
	v_add_f32_e32 v241, 1.0, v241
	v_rcp_f32_e32 v240, v240
	v_rcp_f32_e32 v241, v241
	v_mul_f32_e32 v254, v254, v240
	v_mul_f32_e32 v255, v255, v241
	v_mul_f32_e32 v254, v254, v38
	v_mul_f32_e32 v255, v255, v39
	v_cvt_pk_bf16_f32 v244, v254, v255
	v_lshlrev_b32_e32 v240, 16, v185
	v_and_b32_e32 v241, 0xffff0000, v185
	v_lshlrev_b32_e32 v242, 16, v189
	v_and_b32_e32 v243, 0xffff0000, v189
	v_lshlrev_b32_e32 v252, 16, v193
	v_and_b32_e32 v253, 0xffff0000, v193
	v_fma_f32 v254, v132, v240, v156
	v_fma_f32 v255, v133, v241, v157
	v_fma_f32 v254, v140, v242, v254
	v_fma_f32 v255, v141, v243, v255
	v_fma_f32 v254, v148, v252, v254
	v_fma_f32 v255, v149, v253, v255
	v_mul_f32_e32 v240, 0xbfb8aa3b, v254
	v_mul_f32_e32 v241, 0xbfb8aa3b, v255
	v_exp_f32_e32 v240, v240
	v_exp_f32_e32 v241, v241
	v_add_f32_e32 v240, 1.0, v240
	v_add_f32_e32 v241, 1.0, v241
	v_rcp_f32_e32 v240, v240
	v_rcp_f32_e32 v241, v241
	v_mul_f32_e32 v254, v254, v240
	v_mul_f32_e32 v255, v255, v241
	v_mul_f32_e32 v254, v254, v40
	v_mul_f32_e32 v255, v255, v41
	v_cvt_pk_bf16_f32 v245, v254, v255
	v_lshlrev_b32_e32 v240, 16, v186
	v_and_b32_e32 v241, 0xffff0000, v186
	v_lshlrev_b32_e32 v242, 16, v190
	v_and_b32_e32 v243, 0xffff0000, v190
	v_lshlrev_b32_e32 v252, 16, v194
	v_and_b32_e32 v253, 0xffff0000, v194
	v_fma_f32 v254, v134, v240, v158
	v_fma_f32 v255, v135, v241, v159
	v_fma_f32 v254, v142, v242, v254
	v_fma_f32 v255, v143, v243, v255
	v_fma_f32 v254, v150, v252, v254
	v_fma_f32 v255, v151, v253, v255
	v_mul_f32_e32 v240, 0xbfb8aa3b, v254
	v_mul_f32_e32 v241, 0xbfb8aa3b, v255
	v_exp_f32_e32 v240, v240
	v_exp_f32_e32 v241, v241
	v_add_f32_e32 v240, 1.0, v240
	v_add_f32_e32 v241, 1.0, v241
	v_rcp_f32_e32 v240, v240
	v_rcp_f32_e32 v241, v241
	v_mul_f32_e32 v254, v254, v240
	v_mul_f32_e32 v255, v255, v241
	v_mul_f32_e32 v254, v254, v34
	v_mul_f32_e32 v255, v255, v35
	v_cvt_pk_bf16_f32 v246, v254, v255
	v_lshlrev_b32_e32 v240, 16, v187
	v_and_b32_e32 v241, 0xffff0000, v187
	v_lshlrev_b32_e32 v242, 16, v191
	v_and_b32_e32 v243, 0xffff0000, v191
	v_lshlrev_b32_e32 v252, 16, v195
	v_and_b32_e32 v253, 0xffff0000, v195
	v_fma_f32 v254, v136, v240, v160
	v_fma_f32 v255, v137, v241, v161
	v_fma_f32 v254, v144, v242, v254
	v_fma_f32 v255, v145, v243, v255
	v_fma_f32 v254, v152, v252, v254
	v_fma_f32 v255, v153, v253, v255
	v_mul_f32_e32 v240, 0xbfb8aa3b, v254
	v_mul_f32_e32 v241, 0xbfb8aa3b, v255
	v_exp_f32_e32 v240, v240
	v_exp_f32_e32 v241, v241
	v_add_f32_e32 v240, 1.0, v240
	v_add_f32_e32 v241, 1.0, v241
	v_rcp_f32_e32 v240, v240
	v_rcp_f32_e32 v241, v241
	v_mul_f32_e32 v254, v254, v240
	v_mul_f32_e32 v255, v255, v241
	v_mul_f32_e32 v254, v254, v36
	v_mul_f32_e32 v255, v255, v37
	v_cvt_pk_bf16_f32 v247, v254, v255
	global_store_dwordx4 v[196:197], v[244:247], off
	s_waitcnt vmcnt(1)
	v_add_u32_e32 v183, 0xb0, v176
	v_and_b32_e32 v183, 0x1fff, v183
	v_cmp_eq_u32_e32 vcc, 0x1fff, v183
	v_cndmask_b32_e64 v206, v206, 0, vcc
	v_cndmask_b32_e64 v207, v207, 0, vcc
	v_cndmask_b32_e64 v208, v208, 0, vcc
	v_cndmask_b32_e64 v209, v209, 0, vcc
	v_lshlrev_b32_e32 v240, 16, v198
	v_and_b32_e32 v241, 0xffff0000, v198
	v_lshlrev_b32_e32 v242, 16, v202
	v_and_b32_e32 v243, 0xffff0000, v202
	v_lshlrev_b32_e32 v252, 16, v206
	v_and_b32_e32 v253, 0xffff0000, v206
	v_fma_f32 v254, v130, v240, v154
	v_fma_f32 v255, v131, v241, v155
	v_fma_f32 v254, v138, v242, v254
	v_fma_f32 v255, v139, v243, v255
	v_fma_f32 v254, v146, v252, v254
	v_fma_f32 v255, v147, v253, v255
	v_mul_f32_e32 v240, 0xbfb8aa3b, v254
	v_mul_f32_e32 v241, 0xbfb8aa3b, v255
	v_exp_f32_e32 v240, v240
	v_exp_f32_e32 v241, v241
	v_add_f32_e32 v240, 1.0, v240
	v_add_f32_e32 v241, 1.0, v241
	v_rcp_f32_e32 v240, v240
	v_rcp_f32_e32 v241, v241
	v_mul_f32_e32 v254, v254, v240
	v_mul_f32_e32 v255, v255, v241
	v_mul_f32_e32 v254, v254, v22
	v_mul_f32_e32 v255, v255, v23
	v_cvt_pk_bf16_f32 v248, v254, v255
	v_lshlrev_b32_e32 v240, 16, v199
	v_and_b32_e32 v241, 0xffff0000, v199
	v_lshlrev_b32_e32 v242, 16, v203
	v_and_b32_e32 v243, 0xffff0000, v203
	v_lshlrev_b32_e32 v252, 16, v207
	v_and_b32_e32 v253, 0xffff0000, v207
	v_fma_f32 v254, v132, v240, v156
	v_fma_f32 v255, v133, v241, v157
	v_fma_f32 v254, v140, v242, v254
	v_fma_f32 v255, v141, v243, v255
	v_fma_f32 v254, v148, v252, v254
	v_fma_f32 v255, v149, v253, v255
	v_mul_f32_e32 v240, 0xbfb8aa3b, v254
	v_mul_f32_e32 v241, 0xbfb8aa3b, v255
	v_exp_f32_e32 v240, v240
	v_exp_f32_e32 v241, v241
	v_add_f32_e32 v240, 1.0, v240
	v_add_f32_e32 v241, 1.0, v241
	v_rcp_f32_e32 v240, v240
	v_rcp_f32_e32 v241, v241
	v_mul_f32_e32 v254, v254, v240
	v_mul_f32_e32 v255, v255, v241
	v_mul_f32_e32 v254, v254, v24
	v_mul_f32_e32 v255, v255, v25
	v_cvt_pk_bf16_f32 v249, v254, v255
	v_lshlrev_b32_e32 v240, 16, v200
	v_and_b32_e32 v241, 0xffff0000, v200
	v_lshlrev_b32_e32 v242, 16, v204
	v_and_b32_e32 v243, 0xffff0000, v204
	v_lshlrev_b32_e32 v252, 16, v208
	v_and_b32_e32 v253, 0xffff0000, v208
	v_fma_f32 v254, v134, v240, v158
	v_fma_f32 v255, v135, v241, v159
	v_fma_f32 v254, v142, v242, v254
	v_fma_f32 v255, v143, v243, v255
	v_fma_f32 v254, v150, v252, v254
; DI unsigned pack2(float a, float b) { f32x2_t v = {a, b}; bf16x2_t r = __builtin_convertvector(v, bf16x2_t); return __builtin_bit_cast(unsigned, r); }
; DI float lo2f(unsigned u) { return __uint_as_float(u << 16); }
; DI float hi2f(unsigned u) { return __uint_as_float(u & 0xffff0000u); }
; DI float sigmoidf_(float x) { return __builtin_amdgcn_rcpf(1.f + __builtin_amdgcn_exp2f(-1.4426950408889634f * x)); }
;   DI void operator()(const f32x4 (&acc)[2][2][4][2], const pg8::Unit& u, int wr, int wc, int fr, int fq) const {
;     ...
; #pragma unroll
;         for (int m = 0; m < 4; ++m)
; #pragma unroll
;           for (int bj = 0; bj < 2; ++bj) {
;             const f32x4 v0 = acc[ai][bj][m][0], v1 = acc[ai][bj][m][1];
;             const uint4 g = gs[m][bj];
;             f32x4 q0 = {lo2f(g.x) * v0[0], hi2f(g.x) * v0[1], lo2f(g.y) * v0[2], hi2f(g.y) * v0[3]};
;             f32x4 q1 = {lo2f(g.z) * v1[0], hi2f(g.z) * v1[1], lo2f(g.w) * v1[2], hi2f(g.w) * v1[3]};
;             st8(o0 + (size_t)(row0 + ai * 128 + m * 16) * DFF + col0 + bj * 128, q0, q1);
;           }
; DI void conv_phase(const Params& p, int l) {
;     ...
;     float w0[8], w1[8], w2[8], bb[8];
;     load8f(cw + c0, w0); load8f(cw + DFF + c0, w1); load8f(cw + 2 * DFF + c0, w2); load8f(cb + c0, bb);
;     float prev[8], cur[8], nxt[8];
;     unpack8(rows[0], prev); unpack8(rows[1], cur);
; #pragma unroll
;     for (int i = 0; i < RUN; ++i) {
;       unpack8(rows[i + 2], nxt);
;       float o[8];
; #pragma unroll
;       for (int j = 0; j < 8; ++j) { const float g = w0[j] * prev[j] + w1[j] * cur[j] + w2[j] * nxt[j] + bb[j]; o[j] = g * sigmoidf_(g); }
;       uint4 oo; oo.x = pack2(o[0], o[1]); oo.y = pack2(o[2], o[3]); oo.z = pack2(o[4], o[5]); oo.w = pack2(o[6], o[7]);
	v_fma_f32 v255, v151, v253, v255
	v_mul_f32_e32 v240, 0xbfb8aa3b, v254
	v_mul_f32_e32 v241, 0xbfb8aa3b, v255
	v_exp_f32_e32 v240, v240
	v_exp_f32_e32 v241, v241
	v_add_f32_e32 v240, 1.0, v240
	v_add_f32_e32 v241, 1.0, v241
	v_rcp_f32_e32 v240, v240
	v_rcp_f32_e32 v241, v241
	v_mul_f32_e32 v254, v254, v240
	v_mul_f32_e32 v255, v255, v241
	v_mul_f32_e32 v254, v254, v18
	v_mul_f32_e32 v255, v255, v19
	v_cvt_pk_bf16_f32 v250, v254, v255
	v_lshlrev_b32_e32 v240, 16, v201
	v_and_b32_e32 v241, 0xffff0000, v201
	v_lshlrev_b32_e32 v242, 16, v205
	v_and_b32_e32 v243, 0xffff0000, v205
	v_lshlrev_b32_e32 v252, 16, v209
	v_and_b32_e32 v253, 0xffff0000, v209
	v_fma_f32 v254, v136, v240, v160
	v_fma_f32 v255, v137, v241, v161
	v_fma_f32 v254, v144, v242, v254
	v_fma_f32 v255, v145, v243, v255
	v_fma_f32 v254, v152, v252, v254
	v_fma_f32 v255, v153, v253, v255
	v_mul_f32_e32 v240, 0xbfb8aa3b, v254
	v_mul_f32_e32 v241, 0xbfb8aa3b, v255
	v_exp_f32_e32 v240, v240
	v_exp_f32_e32 v241, v241
	v_add_f32_e32 v240, 1.0, v240
	v_add_f32_e32 v241, 1.0, v241
	v_rcp_f32_e32 v240, v240
	v_rcp_f32_e32 v241, v241
	v_mul_f32_e32 v254, v254, v240
	v_mul_f32_e32 v255, v255, v241
	v_mul_f32_e32 v254, v254, v20
	v_mul_f32_e32 v255, v255, v21
	v_cvt_pk_bf16_f32 v251, v254, v255
	global_store_dwordx4 v[220:221], v[248:251], off
	v_readlane_b32 s98, v237, 62
	v_readlane_b32 s100, v238, 0
	v_readlane_b32 s101, v238, 1
	s_mul_i32 s98, s98, 0xab
	s_bfe_u32 s98, s98, 0x6000a
	s_mul_i32 s99, s98, 0x8400
	s_add_u32 s100, s100, s99
	s_addc_u32 s101, s101, 0
	s_nop 3
	global_load_dwordx4 v[130:133], v182, s[100:101] offset:512
	global_load_dwordx4 v[134:137], v182, s[100:101] offset:528
	s_add_u32 s100, s100, 0x2c00
	s_addc_u32 s101, s101, 0
	global_load_dwordx4 v[138:141], v182, s[100:101] offset:512
	global_load_dwordx4 v[142:145], v182, s[100:101] offset:528
	s_add_u32 s100, s100, 0x2c00
	s_addc_u32 s101, s101, 0
	global_load_dwordx4 v[146:149], v182, s[100:101] offset:512
	global_load_dwordx4 v[150:153], v182, s[100:101] offset:528
	v_readlane_b32 s100, v238, 2
	v_readlane_b32 s101, v238, 3
	s_mul_i32 s99, s98, 0x2c00
	s_add_u32 s100, s100, s99
	s_addc_u32 s101, s101, 0
	s_nop 3
	global_load_dwordx4 v[154:157], v182, s[100:101] offset:512
	global_load_dwordx4 v[158:161], v182, s[100:101] offset:528
	s_mov_b32 s98, 0x1600
	s_mov_b32 s99, 0
	s_mov_b32 s100, 0x16000000
	s_mov_b32 s101, 0
	v_add_u32_e32 v183, -1, v176
	v_mad_i64_i32 v[222:223], s[0:1], v183, s14, v[180:181]
	v_lshl_add_u64 v[224:225], v[222:223], 0, s[98:99]
	v_lshl_add_u64 v[226:227], v[224:225], 0, s[98:99]
	v_lshl_add_u64 v[196:197], v[224:225], 0, s[100:101]
	global_load_dwordx4 v[184:187], v[222:223], off offset:256
	global_load_dwordx4 v[188:191], v[224:225], off offset:256
	global_load_dwordx4 v[192:195], v[226:227], off offset:256
	v_add_u32_e32 v183, 0xf, v176
	v_mad_i64_i32 v[222:223], s[0:1], v183, s14, v[180:181]
	v_lshl_add_u64 v[224:225], v[222:223], 0, s[98:99]
	v_lshl_add_u64 v[226:227], v[224:225], 0, s[98:99]
	v_lshl_add_u64 v[220:221], v[224:225], 0, s[100:101]
	global_load_dwordx4 v[198:201], v[222:223], off offset:256
	global_load_dwordx4 v[202:205], v[224:225], off offset:256
	global_load_dwordx4 v[206:209], v[226:227], off offset:256
	s_waitcnt vmcnt(3)
	v_and_b32_e32 v183, 0x1fff, v176
	v_cmp_eq_u32_e32 vcc, 0, v183
	v_cndmask_b32_e64 v184, v184, 0, vcc
	v_cndmask_b32_e64 v185, v185, 0, vcc
	v_cndmask_b32_e64 v186, v186, 0, vcc
	v_cndmask_b32_e64 v187, v187, 0, vcc
	v_lshlrev_b32_e32 v240, 16, v184
	v_and_b32_e32 v241, 0xffff0000, v184
	v_lshlrev_b32_e32 v242, 16, v188
	v_and_b32_e32 v243, 0xffff0000, v188
	v_lshlrev_b32_e32 v252, 16, v192
	v_and_b32_e32 v253, 0xffff0000, v192
	v_fma_f32 v254, v130, v240, v154
	v_fma_f32 v255, v131, v241, v155
	v_fma_f32 v254, v138, v242, v254
	v_fma_f32 v255, v139, v243, v255
	v_fma_f32 v254, v146, v252, v254
	v_fma_f32 v255, v147, v253, v255
	v_mul_f32_e32 v240, 0xbfb8aa3b, v254
	v_mul_f32_e32 v241, 0xbfb8aa3b, v255
	v_exp_f32_e32 v240, v240
	v_exp_f32_e32 v241, v241
	v_add_f32_e32 v240, 1.0, v240
	v_add_f32_e32 v241, 1.0, v241
	v_rcp_f32_e32 v240, v240
	v_rcp_f32_e32 v241, v241
	v_mul_f32_e32 v254, v254, v240
	v_mul_f32_e32 v255, v255, v241
	v_mul_f32_e32 v254, v254, v110
	v_mul_f32_e32 v255, v255, v111
	v_cvt_pk_bf16_f32 v244, v254, v255
	v_lshlrev_b32_e32 v240, 16, v185
	v_and_b32_e32 v241, 0xffff0000, v185
	v_lshlrev_b32_e32 v242, 16, v189
	v_and_b32_e32 v243, 0xffff0000, v189
	v_lshlrev_b32_e32 v252, 16, v193
	v_and_b32_e32 v253, 0xffff0000, v193
	v_fma_f32 v254, v132, v240, v156
	v_fma_f32 v255, v133, v241, v157
	v_fma_f32 v254, v140, v242, v254
	v_fma_f32 v255, v141, v243, v255
	v_fma_f32 v254, v148, v252, v254
	v_fma_f32 v255, v149, v253, v255
	v_mul_f32_e32 v240, 0xbfb8aa3b, v254
	v_mul_f32_e32 v241, 0xbfb8aa3b, v255
	v_exp_f32_e32 v240, v240
	v_exp_f32_e32 v241, v241
	v_add_f32_e32 v240, 1.0, v240
	v_add_f32_e32 v241, 1.0, v241
	v_rcp_f32_e32 v240, v240
	v_rcp_f32_e32 v241, v241
	v_mul_f32_e32 v254, v254, v240
	v_mul_f32_e32 v255, v255, v241
	v_mul_f32_e32 v254, v254, v112
	v_mul_f32_e32 v255, v255, v113
	v_cvt_pk_bf16_f32 v245, v254, v255
	v_lshlrev_b32_e32 v240, 16, v186
	v_and_b32_e32 v241, 0xffff0000, v186
	v_lshlrev_b32_e32 v242, 16, v190
	v_and_b32_e32 v243, 0xffff0000, v190
	v_lshlrev_b32_e32 v252, 16, v194
	v_and_b32_e32 v253, 0xffff0000, v194
	v_fma_f32 v254, v134, v240, v158
	v_fma_f32 v255, v135, v241, v159
	v_fma_f32 v254, v142, v242, v254
	v_fma_f32 v255, v143, v243, v255
	v_fma_f32 v254, v150, v252, v254
	v_fma_f32 v255, v151, v253, v255
	v_mul_f32_e32 v240, 0xbfb8aa3b, v254
	v_mul_f32_e32 v241, 0xbfb8aa3b, v255
	v_exp_f32_e32 v240, v240
; DI unsigned pack2(float a, float b) { f32x2_t v = {a, b}; bf16x2_t r = __builtin_convertvector(v, bf16x2_t); return __builtin_bit_cast(unsigned, r); }
; DI float lo2f(unsigned u) { return __uint_as_float(u << 16); }
; DI float hi2f(unsigned u) { return __uint_as_float(u & 0xffff0000u); }
; DI float sigmoidf_(float x) { return __builtin_amdgcn_rcpf(1.f + __builtin_amdgcn_exp2f(-1.4426950408889634f * x)); }
;   DI void operator()(const f32x4 (&acc)[2][2][4][2], const pg8::Unit& u, int wr, int wc, int fr, int fq) const {
;     ...
; #pragma unroll
;         for (int m = 0; m < 4; ++m)
; #pragma unroll
;           for (int bj = 0; bj < 2; ++bj) {
;             const f32x4 v0 = acc[ai][bj][m][0], v1 = acc[ai][bj][m][1];
;             const uint4 g = gs[m][bj];
;             f32x4 q0 = {lo2f(g.x) * v0[0], hi2f(g.x) * v0[1], lo2f(g.y) * v0[2], hi2f(g.y) * v0[3]};
;             f32x4 q1 = {lo2f(g.z) * v1[0], hi2f(g.z) * v1[1], lo2f(g.w) * v1[2], hi2f(g.w) * v1[3]};
;             st8(o0 + (size_t)(row0 + ai * 128 + m * 16) * DFF + col0 + bj * 128, q0, q1);
;           }
; DI void conv_phase(const Params& p, int l) {
;     ...
;     for (int i = 0; i < RUN; ++i) {
;       unpack8(rows[i + 2], nxt);
;       float o[8];
; #pragma unroll
;       for (int j = 0; j < 8; ++j) { const float g = w0[j] * prev[j] + w1[j] * cur[j] + w2[j] * nxt[j] + bb[j]; o[j] = g * sigmoidf_(g); }
;       uint4 oo; oo.x = pack2(o[0], o[1]); oo.y = pack2(o[2], o[3]); oo.z = pack2(o[4], o[5]); oo.w = pack2(o[6], o[7]);
	v_exp_f32_e32 v241, v241
	v_add_f32_e32 v240, 1.0, v240
	v_add_f32_e32 v241, 1.0, v241
	v_rcp_f32_e32 v240, v240
	v_rcp_f32_e32 v241, v241
	v_mul_f32_e32 v254, v254, v240
	v_mul_f32_e32 v255, v255, v241
	v_mul_f32_e32 v254, v254, v106
	v_mul_f32_e32 v255, v255, v107
	v_cvt_pk_bf16_f32 v246, v254, v255
	v_lshlrev_b32_e32 v240, 16, v187
	v_and_b32_e32 v241, 0xffff0000, v187
	v_lshlrev_b32_e32 v242, 16, v191
	v_and_b32_e32 v243, 0xffff0000, v191
	v_lshlrev_b32_e32 v252, 16, v195
	v_and_b32_e32 v253, 0xffff0000, v195
	v_fma_f32 v254, v136, v240, v160
	v_fma_f32 v255, v137, v241, v161
	v_fma_f32 v254, v144, v242, v254
	v_fma_f32 v255, v145, v243, v255
	v_fma_f32 v254, v152, v252, v254
	v_fma_f32 v255, v153, v253, v255
	v_mul_f32_e32 v240, 0xbfb8aa3b, v254
	v_mul_f32_e32 v241, 0xbfb8aa3b, v255
	v_exp_f32_e32 v240, v240
	v_exp_f32_e32 v241, v241
	v_add_f32_e32 v240, 1.0, v240
	v_add_f32_e32 v241, 1.0, v241
	v_rcp_f32_e32 v240, v240
	v_rcp_f32_e32 v241, v241
	v_mul_f32_e32 v254, v254, v240
	v_mul_f32_e32 v255, v255, v241
	v_mul_f32_e32 v254, v254, v108
	v_mul_f32_e32 v255, v255, v109
	v_cvt_pk_bf16_f32 v247, v254, v255
	global_store_dwordx4 v[196:197], v[244:247], off offset:256
	v_add_u32_e32 v183, 0x1f, v176
	v_mad_i64_i32 v[222:223], s[0:1], v183, s14, v[180:181]
	v_lshl_add_u64 v[224:225], v[222:223], 0, s[98:99]
	v_lshl_add_u64 v[226:227], v[224:225], 0, s[98:99]
	v_lshl_add_u64 v[196:197], v[224:225], 0, s[100:101]
	global_load_dwordx4 v[184:187], v[222:223], off offset:256
	global_load_dwordx4 v[188:191], v[224:225], off offset:256
	global_load_dwordx4 v[192:195], v[226:227], off offset:256
	s_waitcnt vmcnt(4)
	v_lshlrev_b32_e32 v240, 16, v198
	v_and_b32_e32 v241, 0xffff0000, v198
	v_lshlrev_b32_e32 v242, 16, v202
	v_and_b32_e32 v243, 0xffff0000, v202
	v_lshlrev_b32_e32 v252, 16, v206
	v_and_b32_e32 v253, 0xffff0000, v206
	v_fma_f32 v254, v130, v240, v154
	v_fma_f32 v255, v131, v241, v155
	v_fma_f32 v254, v138, v242, v254
	v_fma_f32 v255, v139, v243, v255
	v_fma_f32 v254, v146, v252, v254
	v_fma_f32 v255, v147, v253, v255
	v_mul_f32_e32 v240, 0xbfb8aa3b, v254
	v_mul_f32_e32 v241, 0xbfb8aa3b, v255
	v_exp_f32_e32 v240, v240
	v_exp_f32_e32 v241, v241
	v_add_f32_e32 v240, 1.0, v240
	v_add_f32_e32 v241, 1.0, v241
	v_rcp_f32_e32 v240, v240
	v_rcp_f32_e32 v241, v241
	v_mul_f32_e32 v254, v254, v240
	v_mul_f32_e32 v255, v255, v241
	v_mul_f32_e32 v254, v254, v94
	v_mul_f32_e32 v255, v255, v95
	v_cvt_pk_bf16_f32 v248, v254, v255
	v_lshlrev_b32_e32 v240, 16, v199
	v_and_b32_e32 v241, 0xffff0000, v199
	v_lshlrev_b32_e32 v242, 16, v203
	v_and_b32_e32 v243, 0xffff0000, v203
	v_lshlrev_b32_e32 v252, 16, v207
	v_and_b32_e32 v253, 0xffff0000, v207
	v_fma_f32 v254, v132, v240, v156
	v_fma_f32 v255, v133, v241, v157
	v_fma_f32 v254, v140, v242, v254
	v_fma_f32 v255, v141, v243, v255
	v_fma_f32 v254, v148, v252, v254
	v_fma_f32 v255, v149, v253, v255
	v_mul_f32_e32 v240, 0xbfb8aa3b, v254
	v_mul_f32_e32 v241, 0xbfb8aa3b, v255
	v_exp_f32_e32 v240, v240
	v_exp_f32_e32 v241, v241
	v_add_f32_e32 v240, 1.0, v240
	v_add_f32_e32 v241, 1.0, v241
	v_rcp_f32_e32 v240, v240
	v_rcp_f32_e32 v241, v241
	v_mul_f32_e32 v254, v254, v240
	v_mul_f32_e32 v255, v255, v241
	v_mul_f32_e32 v254, v254, v96
	v_mul_f32_e32 v255, v255, v97
	v_cvt_pk_bf16_f32 v249, v254, v255
	v_lshlrev_b32_e32 v240, 16, v200
	v_and_b32_e32 v241, 0xffff0000, v200
	v_lshlrev_b32_e32 v242, 16, v204
	v_and_b32_e32 v243, 0xffff0000, v204
	v_lshlrev_b32_e32 v252, 16, v208
	v_and_b32_e32 v253, 0xffff0000, v208
	v_fma_f32 v254, v134, v240, v158
	v_fma_f32 v255, v135, v241, v159
	v_fma_f32 v254, v142, v242, v254
	v_fma_f32 v255, v143, v243, v255
	v_fma_f32 v254, v150, v252, v254
	v_fma_f32 v255, v151, v253, v255
	v_mul_f32_e32 v240, 0xbfb8aa3b, v254
	v_mul_f32_e32 v241, 0xbfb8aa3b, v255
	v_exp_f32_e32 v240, v240
	v_exp_f32_e32 v241, v241
	v_add_f32_e32 v240, 1.0, v240
	v_add_f32_e32 v241, 1.0, v241
	v_rcp_f32_e32 v240, v240
	v_rcp_f32_e32 v241, v241
	v_mul_f32_e32 v254, v254, v240
	v_mul_f32_e32 v255, v255, v241
	v_mul_f32_e32 v254, v254, v90
	v_mul_f32_e32 v255, v255, v91
	v_cvt_pk_bf16_f32 v250, v254, v255
	v_lshlrev_b32_e32 v240, 16, v201
	v_and_b32_e32 v241, 0xffff0000, v201
	v_lshlrev_b32_e32 v242, 16, v205
	v_and_b32_e32 v243, 0xffff0000, v205
	v_lshlrev_b32_e32 v252, 16, v209
	v_and_b32_e32 v253, 0xffff0000, v209
	v_fma_f32 v254, v136, v240, v160
	v_fma_f32 v255, v137, v241, v161
	v_fma_f32 v254, v144, v242, v254
	v_fma_f32 v255, v145, v243, v255
	v_fma_f32 v254, v152, v252, v254
	v_fma_f32 v255, v153, v253, v255
	v_mul_f32_e32 v240, 0xbfb8aa3b, v254
	v_mul_f32_e32 v241, 0xbfb8aa3b, v255
	v_exp_f32_e32 v240, v240
	v_exp_f32_e32 v241, v241
	v_add_f32_e32 v240, 1.0, v240
	v_add_f32_e32 v241, 1.0, v241
	v_rcp_f32_e32 v240, v240
	v_rcp_f32_e32 v241, v241
	v_mul_f32_e32 v254, v254, v240
	v_mul_f32_e32 v255, v255, v241
	v_mul_f32_e32 v254, v254, v92
	v_mul_f32_e32 v255, v255, v93
	v_cvt_pk_bf16_f32 v251, v254, v255
	global_store_dwordx4 v[220:221], v[248:251], off offset:256
	v_add_u32_e32 v183, 0x2f, v176
	v_mad_i64_i32 v[222:223], s[0:1], v183, s14, v[180:181]
	v_lshl_add_u64 v[224:225], v[222:223], 0, s[98:99]
	v_lshl_add_u64 v[226:227], v[224:225], 0, s[98:99]
	v_lshl_add_u64 v[220:221], v[224:225], 0, s[100:101]
	global_load_dwordx4 v[198:201], v[222:223], off offset:256
	global_load_dwordx4 v[202:205], v[224:225], off offset:256
	global_load_dwordx4 v[206:209], v[226:227], off offset:256
	s_waitcnt vmcnt(4)
; DI unsigned pack2(float a, float b) { f32x2_t v = {a, b}; bf16x2_t r = __builtin_convertvector(v, bf16x2_t); return __builtin_bit_cast(unsigned, r); }
; DI float lo2f(unsigned u) { return __uint_as_float(u << 16); }
; DI float hi2f(unsigned u) { return __uint_as_float(u & 0xffff0000u); }
; DI float sigmoidf_(float x) { return __builtin_amdgcn_rcpf(1.f + __builtin_amdgcn_exp2f(-1.4426950408889634f * x)); }
;   DI void operator()(const f32x4 (&acc)[2][2][4][2], const pg8::Unit& u, int wr, int wc, int fr, int fq) const {
;     ...
; #pragma unroll
;         for (int m = 0; m < 4; ++m)
; #pragma unroll
;           for (int bj = 0; bj < 2; ++bj) {
;             const f32x4 v0 = acc[ai][bj][m][0], v1 = acc[ai][bj][m][1];
;             const uint4 g = gs[m][bj];
;             f32x4 q0 = {lo2f(g.x) * v0[0], hi2f(g.x) * v0[1], lo2f(g.y) * v0[2], hi2f(g.y) * v0[3]};
;             f32x4 q1 = {lo2f(g.z) * v1[0], hi2f(g.z) * v1[1], lo2f(g.w) * v1[2], hi2f(g.w) * v1[3]};
;             st8(o0 + (size_t)(row0 + ai * 128 + m * 16) * DFF + col0 + bj * 128, q0, q1);
;           }
; DI void conv_phase(const Params& p, int l) {
;     ...
;     for (int i = 0; i < RUN; ++i) {
;       unpack8(rows[i + 2], nxt);
;       float o[8];
; #pragma unroll
;       for (int j = 0; j < 8; ++j) { const float g = w0[j] * prev[j] + w1[j] * cur[j] + w2[j] * nxt[j] + bb[j]; o[j] = g * sigmoidf_(g); }
;       uint4 oo; oo.x = pack2(o[0], o[1]); oo.y = pack2(o[2], o[3]); oo.z = pack2(o[4], o[5]); oo.w = pack2(o[6], o[7]);
	v_lshlrev_b32_e32 v240, 16, v184
	v_and_b32_e32 v241, 0xffff0000, v184
	v_lshlrev_b32_e32 v242, 16, v188
	v_and_b32_e32 v243, 0xffff0000, v188
	v_lshlrev_b32_e32 v252, 16, v192
	v_and_b32_e32 v253, 0xffff0000, v192
	v_fma_f32 v254, v130, v240, v154
	v_fma_f32 v255, v131, v241, v155
	v_fma_f32 v254, v138, v242, v254
	v_fma_f32 v255, v139, v243, v255
	v_fma_f32 v254, v146, v252, v254
	v_fma_f32 v255, v147, v253, v255
	v_mul_f32_e32 v240, 0xbfb8aa3b, v254
	v_mul_f32_e32 v241, 0xbfb8aa3b, v255
	v_exp_f32_e32 v240, v240
	v_exp_f32_e32 v241, v241
	v_add_f32_e32 v240, 1.0, v240
	v_add_f32_e32 v241, 1.0, v241
	v_rcp_f32_e32 v240, v240
	v_rcp_f32_e32 v241, v241
	v_mul_f32_e32 v254, v254, v240
	v_mul_f32_e32 v255, v255, v241
	v_mul_f32_e32 v254, v254, v78
	v_mul_f32_e32 v255, v255, v79
	v_cvt_pk_bf16_f32 v244, v254, v255
	v_lshlrev_b32_e32 v240, 16, v185
	v_and_b32_e32 v241, 0xffff0000, v185
	v_lshlrev_b32_e32 v242, 16, v189
	v_and_b32_e32 v243, 0xffff0000, v189
	v_lshlrev_b32_e32 v252, 16, v193
	v_and_b32_e32 v253, 0xffff0000, v193
	v_fma_f32 v254, v132, v240, v156
	v_fma_f32 v255, v133, v241, v157
	v_fma_f32 v254, v140, v242, v254
	v_fma_f32 v255, v141, v243, v255
	v_fma_f32 v254, v148, v252, v254
	v_fma_f32 v255, v149, v253, v255
	v_mul_f32_e32 v240, 0xbfb8aa3b, v254
	v_mul_f32_e32 v241, 0xbfb8aa3b, v255
	v_exp_f32_e32 v240, v240
	v_exp_f32_e32 v241, v241
	v_add_f32_e32 v240, 1.0, v240
	v_add_f32_e32 v241, 1.0, v241
	v_rcp_f32_e32 v240, v240
	v_rcp_f32_e32 v241, v241
	v_mul_f32_e32 v254, v254, v240
	v_mul_f32_e32 v255, v255, v241
	v_mul_f32_e32 v254, v254, v80
	v_mul_f32_e32 v255, v255, v81
	v_cvt_pk_bf16_f32 v245, v254, v255
	v_lshlrev_b32_e32 v240, 16, v186
	v_and_b32_e32 v241, 0xffff0000, v186
	v_lshlrev_b32_e32 v242, 16, v190
	v_and_b32_e32 v243, 0xffff0000, v190
	v_lshlrev_b32_e32 v252, 16, v194
	v_and_b32_e32 v253, 0xffff0000, v194
	v_fma_f32 v254, v134, v240, v158
	v_fma_f32 v255, v135, v241, v159
	v_fma_f32 v254, v142, v242, v254
	v_fma_f32 v255, v143, v243, v255
	v_fma_f32 v254, v150, v252, v254
	v_fma_f32 v255, v151, v253, v255
	v_mul_f32_e32 v240, 0xbfb8aa3b, v254
	v_mul_f32_e32 v241, 0xbfb8aa3b, v255
	v_exp_f32_e32 v240, v240
	v_exp_f32_e32 v241, v241
	v_add_f32_e32 v240, 1.0, v240
	v_add_f32_e32 v241, 1.0, v241
	v_rcp_f32_e32 v240, v240
	v_rcp_f32_e32 v241, v241
	v_mul_f32_e32 v254, v254, v240
	v_mul_f32_e32 v255, v255, v241
	v_mul_f32_e32 v254, v254, v74
	v_mul_f32_e32 v255, v255, v75
	v_cvt_pk_bf16_f32 v246, v254, v255
	v_lshlrev_b32_e32 v240, 16, v187
	v_and_b32_e32 v241, 0xffff0000, v187
	v_lshlrev_b32_e32 v242, 16, v191
	v_and_b32_e32 v243, 0xffff0000, v191
	v_lshlrev_b32_e32 v252, 16, v195
	v_and_b32_e32 v253, 0xffff0000, v195
	v_fma_f32 v254, v136, v240, v160
	v_fma_f32 v255, v137, v241, v161
	v_fma_f32 v254, v144, v242, v254
	v_fma_f32 v255, v145, v243, v255
	v_fma_f32 v254, v152, v252, v254
	v_fma_f32 v255, v153, v253, v255
	v_mul_f32_e32 v240, 0xbfb8aa3b, v254
	v_mul_f32_e32 v241, 0xbfb8aa3b, v255
	v_exp_f32_e32 v240, v240
	v_exp_f32_e32 v241, v241
	v_add_f32_e32 v240, 1.0, v240
	v_add_f32_e32 v241, 1.0, v241
	v_rcp_f32_e32 v240, v240
	v_rcp_f32_e32 v241, v241
	v_mul_f32_e32 v254, v254, v240
	v_mul_f32_e32 v255, v255, v241
	v_mul_f32_e32 v254, v254, v76
	v_mul_f32_e32 v255, v255, v77
	v_cvt_pk_bf16_f32 v247, v254, v255
	global_store_dwordx4 v[196:197], v[244:247], off offset:256
	v_add_u32_e32 v183, 0x7f, v176
	v_mad_i64_i32 v[222:223], s[0:1], v183, s14, v[180:181]
	v_lshl_add_u64 v[224:225], v[222:223], 0, s[98:99]
	v_lshl_add_u64 v[226:227], v[224:225], 0, s[98:99]
	v_lshl_add_u64 v[196:197], v[224:225], 0, s[100:101]
	global_load_dwordx4 v[184:187], v[222:223], off offset:256
	global_load_dwordx4 v[188:191], v[224:225], off offset:256
	global_load_dwordx4 v[192:195], v[226:227], off offset:256
	s_waitcnt vmcnt(4)
	v_lshlrev_b32_e32 v240, 16, v198
	v_and_b32_e32 v241, 0xffff0000, v198
	v_lshlrev_b32_e32 v242, 16, v202
	v_and_b32_e32 v243, 0xffff0000, v202
	v_lshlrev_b32_e32 v252, 16, v206
	v_and_b32_e32 v253, 0xffff0000, v206
	v_fma_f32 v254, v130, v240, v154
	v_fma_f32 v255, v131, v241, v155
	v_fma_f32 v254, v138, v242, v254
	v_fma_f32 v255, v139, v243, v255
	v_fma_f32 v254, v146, v252, v254
	v_fma_f32 v255, v147, v253, v255
	v_mul_f32_e32 v240, 0xbfb8aa3b, v254
	v_mul_f32_e32 v241, 0xbfb8aa3b, v255
	v_exp_f32_e32 v240, v240
	v_exp_f32_e32 v241, v241
	v_add_f32_e32 v240, 1.0, v240
	v_add_f32_e32 v241, 1.0, v241
	v_rcp_f32_e32 v240, v240
	v_rcp_f32_e32 v241, v241
	v_mul_f32_e32 v254, v254, v240
	v_mul_f32_e32 v255, v255, v241
	v_mul_f32_e32 v254, v254, v70
	v_mul_f32_e32 v255, v255, v71
	v_cvt_pk_bf16_f32 v248, v254, v255
	v_lshlrev_b32_e32 v240, 16, v199
	v_and_b32_e32 v241, 0xffff0000, v199
	v_lshlrev_b32_e32 v242, 16, v203
	v_and_b32_e32 v243, 0xffff0000, v203
	v_lshlrev_b32_e32 v252, 16, v207
	v_and_b32_e32 v253, 0xffff0000, v207
	v_fma_f32 v254, v132, v240, v156
	v_fma_f32 v255, v133, v241, v157
	v_fma_f32 v254, v140, v242, v254
	v_fma_f32 v255, v141, v243, v255
	v_fma_f32 v254, v148, v252, v254
	v_fma_f32 v255, v149, v253, v255
	v_mul_f32_e32 v240, 0xbfb8aa3b, v254
	v_mul_f32_e32 v241, 0xbfb8aa3b, v255
	v_exp_f32_e32 v240, v240
	v_exp_f32_e32 v241, v241
	v_add_f32_e32 v240, 1.0, v240
	v_add_f32_e32 v241, 1.0, v241
	v_rcp_f32_e32 v240, v240
	v_rcp_f32_e32 v241, v241
	v_mul_f32_e32 v254, v254, v240
	v_mul_f32_e32 v255, v255, v241
	v_mul_f32_e32 v254, v254, v72
	v_mul_f32_e32 v255, v255, v73
	v_cvt_pk_bf16_f32 v249, v254, v255
	v_lshlrev_b32_e32 v240, 16, v200
	v_and_b32_e32 v241, 0xffff0000, v200
	v_lshlrev_b32_e32 v242, 16, v204
	v_and_b32_e32 v243, 0xffff0000, v204
	v_lshlrev_b32_e32 v252, 16, v208
; DI unsigned pack2(float a, float b) { f32x2_t v = {a, b}; bf16x2_t r = __builtin_convertvector(v, bf16x2_t); return __builtin_bit_cast(unsigned, r); }
; DI float lo2f(unsigned u) { return __uint_as_float(u << 16); }
; DI float hi2f(unsigned u) { return __uint_as_float(u & 0xffff0000u); }
; DI float sigmoidf_(float x) { return __builtin_amdgcn_rcpf(1.f + __builtin_amdgcn_exp2f(-1.4426950408889634f * x)); }
;   DI void operator()(const f32x4 (&acc)[2][2][4][2], const pg8::Unit& u, int wr, int wc, int fr, int fq) const {
;     ...
; #pragma unroll
;         for (int m = 0; m < 4; ++m)
; #pragma unroll
;           for (int bj = 0; bj < 2; ++bj) {
;             const f32x4 v0 = acc[ai][bj][m][0], v1 = acc[ai][bj][m][1];
;             const uint4 g = gs[m][bj];
;             f32x4 q0 = {lo2f(g.x) * v0[0], hi2f(g.x) * v0[1], lo2f(g.y) * v0[2], hi2f(g.y) * v0[3]};
;             f32x4 q1 = {lo2f(g.z) * v1[0], hi2f(g.z) * v1[1], lo2f(g.w) * v1[2], hi2f(g.w) * v1[3]};
;             st8(o0 + (size_t)(row0 + ai * 128 + m * 16) * DFF + col0 + bj * 128, q0, q1);
;           }
; DI void conv_phase(const Params& p, int l) {
;     ...
;     for (int i = 0; i < RUN; ++i) {
;       unpack8(rows[i + 2], nxt);
;       float o[8];
; #pragma unroll
;       for (int j = 0; j < 8; ++j) { const float g = w0[j] * prev[j] + w1[j] * cur[j] + w2[j] * nxt[j] + bb[j]; o[j] = g * sigmoidf_(g); }
;       uint4 oo; oo.x = pack2(o[0], o[1]); oo.y = pack2(o[2], o[3]); oo.z = pack2(o[4], o[5]); oo.w = pack2(o[6], o[7]);
	v_and_b32_e32 v253, 0xffff0000, v208
	v_fma_f32 v254, v134, v240, v158
	v_fma_f32 v255, v135, v241, v159
	v_fma_f32 v254, v142, v242, v254
	v_fma_f32 v255, v143, v243, v255
	v_fma_f32 v254, v150, v252, v254
	v_fma_f32 v255, v151, v253, v255
	v_mul_f32_e32 v240, 0xbfb8aa3b, v254
	v_mul_f32_e32 v241, 0xbfb8aa3b, v255
	v_exp_f32_e32 v240, v240
	v_exp_f32_e32 v241, v241
	v_add_f32_e32 v240, 1.0, v240
	v_add_f32_e32 v241, 1.0, v241
	v_rcp_f32_e32 v240, v240
	v_rcp_f32_e32 v241, v241
	v_mul_f32_e32 v254, v254, v240
	v_mul_f32_e32 v255, v255, v241
	v_mul_f32_e32 v254, v254, v66
	v_mul_f32_e32 v255, v255, v67
	v_cvt_pk_bf16_f32 v250, v254, v255
	v_lshlrev_b32_e32 v240, 16, v201
	v_and_b32_e32 v241, 0xffff0000, v201
	v_lshlrev_b32_e32 v242, 16, v205
	v_and_b32_e32 v243, 0xffff0000, v205
	v_lshlrev_b32_e32 v252, 16, v209
	v_and_b32_e32 v253, 0xffff0000, v209
	v_fma_f32 v254, v136, v240, v160
	v_fma_f32 v255, v137, v241, v161
	v_fma_f32 v254, v144, v242, v254
	v_fma_f32 v255, v145, v243, v255
	v_fma_f32 v254, v152, v252, v254
	v_fma_f32 v255, v153, v253, v255
	v_mul_f32_e32 v240, 0xbfb8aa3b, v254
	v_mul_f32_e32 v241, 0xbfb8aa3b, v255
	v_exp_f32_e32 v240, v240
	v_exp_f32_e32 v241, v241
	v_add_f32_e32 v240, 1.0, v240
	v_add_f32_e32 v241, 1.0, v241
	v_rcp_f32_e32 v240, v240
	v_rcp_f32_e32 v241, v241
	v_mul_f32_e32 v254, v254, v240
	v_mul_f32_e32 v255, v255, v241
	v_mul_f32_e32 v254, v254, v68
	v_mul_f32_e32 v255, v255, v69
	v_cvt_pk_bf16_f32 v251, v254, v255
	global_store_dwordx4 v[220:221], v[248:251], off offset:256
	v_add_u32_e32 v183, 0x8f, v176
	v_mad_i64_i32 v[222:223], s[0:1], v183, s14, v[180:181]
	v_lshl_add_u64 v[224:225], v[222:223], 0, s[98:99]
	v_lshl_add_u64 v[226:227], v[224:225], 0, s[98:99]
	v_lshl_add_u64 v[220:221], v[224:225], 0, s[100:101]
	global_load_dwordx4 v[198:201], v[222:223], off offset:256
	global_load_dwordx4 v[202:205], v[224:225], off offset:256
	global_load_dwordx4 v[206:209], v[226:227], off offset:256
	s_waitcnt vmcnt(4)
	v_lshlrev_b32_e32 v240, 16, v184
	v_and_b32_e32 v241, 0xffff0000, v184
	v_lshlrev_b32_e32 v242, 16, v188
	v_and_b32_e32 v243, 0xffff0000, v188
	v_lshlrev_b32_e32 v252, 16, v192
	v_and_b32_e32 v253, 0xffff0000, v192
	v_fma_f32 v254, v130, v240, v154
	v_fma_f32 v255, v131, v241, v155
	v_fma_f32 v254, v138, v242, v254
	v_fma_f32 v255, v139, v243, v255
	v_fma_f32 v254, v146, v252, v254
	v_fma_f32 v255, v147, v253, v255
	v_mul_f32_e32 v240, 0xbfb8aa3b, v254
	v_mul_f32_e32 v241, 0xbfb8aa3b, v255
	v_exp_f32_e32 v240, v240
	v_exp_f32_e32 v241, v241
	v_add_f32_e32 v240, 1.0, v240
	v_add_f32_e32 v241, 1.0, v241
	v_rcp_f32_e32 v240, v240
	v_rcp_f32_e32 v241, v241
	v_mul_f32_e32 v254, v254, v240
	v_mul_f32_e32 v255, v255, v241
	v_mul_f32_e32 v254, v254, v46
	v_mul_f32_e32 v255, v255, v47
	v_cvt_pk_bf16_f32 v244, v254, v255
	v_lshlrev_b32_e32 v240, 16, v185
	v_and_b32_e32 v241, 0xffff0000, v185
	v_lshlrev_b32_e32 v242, 16, v189
	v_and_b32_e32 v243, 0xffff0000, v189
	v_lshlrev_b32_e32 v252, 16, v193
	v_and_b32_e32 v253, 0xffff0000, v193
	v_fma_f32 v254, v132, v240, v156
	v_fma_f32 v255, v133, v241, v157
	v_fma_f32 v254, v140, v242, v254
	v_fma_f32 v255, v141, v243, v255
	v_fma_f32 v254, v148, v252, v254
	v_fma_f32 v255, v149, v253, v255
	v_mul_f32_e32 v240, 0xbfb8aa3b, v254
	v_mul_f32_e32 v241, 0xbfb8aa3b, v255
	v_exp_f32_e32 v240, v240
	v_exp_f32_e32 v241, v241
	v_add_f32_e32 v240, 1.0, v240
	v_add_f32_e32 v241, 1.0, v241
	v_rcp_f32_e32 v240, v240
	v_rcp_f32_e32 v241, v241
	v_mul_f32_e32 v254, v254, v240
	v_mul_f32_e32 v255, v255, v241
	v_mul_f32_e32 v254, v254, v48
	v_mul_f32_e32 v255, v255, v49
	v_cvt_pk_bf16_f32 v245, v254, v255
	v_lshlrev_b32_e32 v240, 16, v186
	v_and_b32_e32 v241, 0xffff0000, v186
	v_lshlrev_b32_e32 v242, 16, v190
	v_and_b32_e32 v243, 0xffff0000, v190
	v_lshlrev_b32_e32 v252, 16, v194
	v_and_b32_e32 v253, 0xffff0000, v194
	v_fma_f32 v254, v134, v240, v158
	v_fma_f32 v255, v135, v241, v159
	v_fma_f32 v254, v142, v242, v254
	v_fma_f32 v255, v143, v243, v255
	v_fma_f32 v254, v150, v252, v254
	v_fma_f32 v255, v151, v253, v255
	v_mul_f32_e32 v240, 0xbfb8aa3b, v254
	v_mul_f32_e32 v241, 0xbfb8aa3b, v255
	v_exp_f32_e32 v240, v240
	v_exp_f32_e32 v241, v241
	v_add_f32_e32 v240, 1.0, v240
	v_add_f32_e32 v241, 1.0, v241
	v_rcp_f32_e32 v240, v240
	v_rcp_f32_e32 v241, v241
	v_mul_f32_e32 v254, v254, v240
	v_mul_f32_e32 v255, v255, v241
	v_mul_f32_e32 v254, v254, v42
	v_mul_f32_e32 v255, v255, v43
	v_cvt_pk_bf16_f32 v246, v254, v255
	v_lshlrev_b32_e32 v240, 16, v187
	v_and_b32_e32 v241, 0xffff0000, v187
	v_lshlrev_b32_e32 v242, 16, v191
	v_and_b32_e32 v243, 0xffff0000, v191
	v_lshlrev_b32_e32 v252, 16, v195
	v_and_b32_e32 v253, 0xffff0000, v195
	v_fma_f32 v254, v136, v240, v160
	v_fma_f32 v255, v137, v241, v161
	v_fma_f32 v254, v144, v242, v254
	v_fma_f32 v255, v145, v243, v255
	v_fma_f32 v254, v152, v252, v254
	v_fma_f32 v255, v153, v253, v255
	v_mul_f32_e32 v240, 0xbfb8aa3b, v254
	v_mul_f32_e32 v241, 0xbfb8aa3b, v255
	v_exp_f32_e32 v240, v240
	v_exp_f32_e32 v241, v241
	v_add_f32_e32 v240, 1.0, v240
	v_add_f32_e32 v241, 1.0, v241
	v_rcp_f32_e32 v240, v240
	v_rcp_f32_e32 v241, v241
	v_mul_f32_e32 v254, v254, v240
	v_mul_f32_e32 v255, v255, v241
	v_mul_f32_e32 v254, v254, v44
	v_mul_f32_e32 v255, v255, v45
	v_cvt_pk_bf16_f32 v247, v254, v255
	global_store_dwordx4 v[196:197], v[244:247], off offset:256
	v_add_u32_e32 v183, 0x9f, v176
	v_mad_i64_i32 v[222:223], s[0:1], v183, s14, v[180:181]
	v_lshl_add_u64 v[224:225], v[222:223], 0, s[98:99]
	v_lshl_add_u64 v[226:227], v[224:225], 0, s[98:99]
	v_lshl_add_u64 v[196:197], v[224:225], 0, s[100:101]
	global_load_dwordx4 v[184:187], v[222:223], off offset:256
	global_load_dwordx4 v[188:191], v[224:225], off offset:256
	global_load_dwordx4 v[192:195], v[226:227], off offset:256
	s_waitcnt vmcnt(4)
; DI unsigned pack2(float a, float b) { f32x2_t v = {a, b}; bf16x2_t r = __builtin_convertvector(v, bf16x2_t); return __builtin_bit_cast(unsigned, r); }
; DI float lo2f(unsigned u) { return __uint_as_float(u << 16); }
; DI float hi2f(unsigned u) { return __uint_as_float(u & 0xffff0000u); }
; DI float sigmoidf_(float x) { return __builtin_amdgcn_rcpf(1.f + __builtin_amdgcn_exp2f(-1.4426950408889634f * x)); }
;   DI void operator()(const f32x4 (&acc)[2][2][4][2], const pg8::Unit& u, int wr, int wc, int fr, int fq) const {
;     ...
; #pragma unroll
;         for (int m = 0; m < 4; ++m)
; #pragma unroll
;           for (int bj = 0; bj < 2; ++bj) {
;             const f32x4 v0 = acc[ai][bj][m][0], v1 = acc[ai][bj][m][1];
;             const uint4 g = gs[m][bj];
;             f32x4 q0 = {lo2f(g.x) * v0[0], hi2f(g.x) * v0[1], lo2f(g.y) * v0[2], hi2f(g.y) * v0[3]};
;             f32x4 q1 = {lo2f(g.z) * v1[0], hi2f(g.z) * v1[1], lo2f(g.w) * v1[2], hi2f(g.w) * v1[3]};
;             st8(o0 + (size_t)(row0 + ai * 128 + m * 16) * DFF + col0 + bj * 128, q0, q1);
;           }
; DI void conv_phase(const Params& p, int l) {
;     ...
;     for (int i = 0; i < RUN; ++i) {
;       unpack8(rows[i + 2], nxt);
;       float o[8];
; #pragma unroll
;       for (int j = 0; j < 8; ++j) { const float g = w0[j] * prev[j] + w1[j] * cur[j] + w2[j] * nxt[j] + bb[j]; o[j] = g * sigmoidf_(g); }
;       uint4 oo; oo.x = pack2(o[0], o[1]); oo.y = pack2(o[2], o[3]); oo.z = pack2(o[4], o[5]); oo.w = pack2(o[6], o[7]);
	v_lshlrev_b32_e32 v240, 16, v198
	v_and_b32_e32 v241, 0xffff0000, v198
	v_lshlrev_b32_e32 v242, 16, v202
	v_and_b32_e32 v243, 0xffff0000, v202
	v_lshlrev_b32_e32 v252, 16, v206
	v_and_b32_e32 v253, 0xffff0000, v206
	v_fma_f32 v254, v130, v240, v154
	v_fma_f32 v255, v131, v241, v155
	v_fma_f32 v254, v138, v242, v254
	v_fma_f32 v255, v139, v243, v255
	v_fma_f32 v254, v146, v252, v254
	v_fma_f32 v255, v147, v253, v255
	v_mul_f32_e32 v240, 0xbfb8aa3b, v254
	v_mul_f32_e32 v241, 0xbfb8aa3b, v255
	v_exp_f32_e32 v240, v240
	v_exp_f32_e32 v241, v241
	v_add_f32_e32 v240, 1.0, v240
	v_add_f32_e32 v241, 1.0, v241
	v_rcp_f32_e32 v240, v240
	v_rcp_f32_e32 v241, v241
	v_mul_f32_e32 v254, v254, v240
	v_mul_f32_e32 v255, v255, v241
	v_mul_f32_e32 v254, v254, v30
	v_mul_f32_e32 v255, v255, v31
	v_cvt_pk_bf16_f32 v248, v254, v255
	v_lshlrev_b32_e32 v240, 16, v199
	v_and_b32_e32 v241, 0xffff0000, v199
	v_lshlrev_b32_e32 v242, 16, v203
	v_and_b32_e32 v243, 0xffff0000, v203
	v_lshlrev_b32_e32 v252, 16, v207
	v_and_b32_e32 v253, 0xffff0000, v207
	v_fma_f32 v254, v132, v240, v156
	v_fma_f32 v255, v133, v241, v157
	v_fma_f32 v254, v140, v242, v254
	v_fma_f32 v255, v141, v243, v255
	v_fma_f32 v254, v148, v252, v254
	v_fma_f32 v255, v149, v253, v255
	v_mul_f32_e32 v240, 0xbfb8aa3b, v254
	v_mul_f32_e32 v241, 0xbfb8aa3b, v255
	v_exp_f32_e32 v240, v240
	v_exp_f32_e32 v241, v241
	v_add_f32_e32 v240, 1.0, v240
	v_add_f32_e32 v241, 1.0, v241
	v_rcp_f32_e32 v240, v240
	v_rcp_f32_e32 v241, v241
	v_mul_f32_e32 v254, v254, v240
	v_mul_f32_e32 v255, v255, v241
	v_mul_f32_e32 v254, v254, v32
	v_mul_f32_e32 v255, v255, v33
	v_cvt_pk_bf16_f32 v249, v254, v255
	v_lshlrev_b32_e32 v240, 16, v200
	v_and_b32_e32 v241, 0xffff0000, v200
	v_lshlrev_b32_e32 v242, 16, v204
	v_and_b32_e32 v243, 0xffff0000, v204
	v_lshlrev_b32_e32 v252, 16, v208
	v_and_b32_e32 v253, 0xffff0000, v208
	v_fma_f32 v254, v134, v240, v158
	v_fma_f32 v255, v135, v241, v159
	v_fma_f32 v254, v142, v242, v254
	v_fma_f32 v255, v143, v243, v255
	v_fma_f32 v254, v150, v252, v254
	v_fma_f32 v255, v151, v253, v255
	v_mul_f32_e32 v240, 0xbfb8aa3b, v254
	v_mul_f32_e32 v241, 0xbfb8aa3b, v255
	v_exp_f32_e32 v240, v240
	v_exp_f32_e32 v241, v241
	v_add_f32_e32 v240, 1.0, v240
	v_add_f32_e32 v241, 1.0, v241
	v_rcp_f32_e32 v240, v240
	v_rcp_f32_e32 v241, v241
	v_mul_f32_e32 v254, v254, v240
	v_mul_f32_e32 v255, v255, v241
	v_mul_f32_e32 v254, v254, v26
	v_mul_f32_e32 v255, v255, v27
	v_cvt_pk_bf16_f32 v250, v254, v255
	v_lshlrev_b32_e32 v240, 16, v201
	v_and_b32_e32 v241, 0xffff0000, v201
	v_lshlrev_b32_e32 v242, 16, v205
	v_and_b32_e32 v243, 0xffff0000, v205
	v_lshlrev_b32_e32 v252, 16, v209
	v_and_b32_e32 v253, 0xffff0000, v209
	v_fma_f32 v254, v136, v240, v160
	v_fma_f32 v255, v137, v241, v161
	v_fma_f32 v254, v144, v242, v254
	v_fma_f32 v255, v145, v243, v255
	v_fma_f32 v254, v152, v252, v254
	v_fma_f32 v255, v153, v253, v255
	v_mul_f32_e32 v240, 0xbfb8aa3b, v254
	v_mul_f32_e32 v241, 0xbfb8aa3b, v255
	v_exp_f32_e32 v240, v240
	v_exp_f32_e32 v241, v241
	v_add_f32_e32 v240, 1.0, v240
	v_add_f32_e32 v241, 1.0, v241
	v_rcp_f32_e32 v240, v240
	v_rcp_f32_e32 v241, v241
	v_mul_f32_e32 v254, v254, v240
	v_mul_f32_e32 v255, v255, v241
	v_mul_f32_e32 v254, v254, v28
	v_mul_f32_e32 v255, v255, v29
	v_cvt_pk_bf16_f32 v251, v254, v255
	global_store_dwordx4 v[220:221], v[248:251], off offset:256
	v_add_u32_e32 v183, 0xaf, v176
	v_mad_i64_i32 v[222:223], s[0:1], v183, s14, v[180:181]
	v_lshl_add_u64 v[224:225], v[222:223], 0, s[98:99]
	v_lshl_add_u64 v[226:227], v[224:225], 0, s[98:99]
	v_lshl_add_u64 v[220:221], v[224:225], 0, s[100:101]
	global_load_dwordx4 v[198:201], v[222:223], off offset:256
	global_load_dwordx4 v[202:205], v[224:225], off offset:256
	global_load_dwordx4 v[206:209], v[226:227], off offset:256
	s_waitcnt vmcnt(4)
; DI unsigned pack2(float a, float b) { f32x2_t v = {a, b}; bf16x2_t r = __builtin_convertvector(v, bf16x2_t); return __builtin_bit_cast(unsigned, r); }
; DI float lo2f(unsigned u) { return __uint_as_float(u << 16); }
; DI float hi2f(unsigned u) { return __uint_as_float(u & 0xffff0000u); }
; DI float sigmoidf_(float x) { return __builtin_amdgcn_rcpf(1.f + __builtin_amdgcn_exp2f(-1.4426950408889634f * x)); }
;   DI void operator()(const f32x4 (&acc)[2][2][4][2], const pg8::Unit& u, int wr, int wc, int fr, int fq) const {
;     ...
; #pragma unroll
;         for (int m = 0; m < 4; ++m)
; #pragma unroll
;           for (int bj = 0; bj < 2; ++bj) {
;             const f32x4 v0 = acc[ai][bj][m][0], v1 = acc[ai][bj][m][1];
;             const uint4 g = gs[m][bj];
;             f32x4 q0 = {lo2f(g.x) * v0[0], hi2f(g.x) * v0[1], lo2f(g.y) * v0[2], hi2f(g.y) * v0[3]};
;             f32x4 q1 = {lo2f(g.z) * v1[0], hi2f(g.z) * v1[1], lo2f(g.w) * v1[2], hi2f(g.w) * v1[3]};
;             st8(o0 + (size_t)(row0 + ai * 128 + m * 16) * DFF + col0 + bj * 128, q0, q1);
;           }
; DI void conv_phase(const Params& p, int l) {
;     ...
;     for (int i = 0; i < RUN; ++i) {
;       unpack8(rows[i + 2], nxt);
;       float o[8];
; #pragma unroll
;       for (int j = 0; j < 8; ++j) { const float g = w0[j] * prev[j] + w1[j] * cur[j] + w2[j] * nxt[j] + bb[j]; o[j] = g * sigmoidf_(g); }
;       uint4 oo; oo.x = pack2(o[0], o[1]); oo.y = pack2(o[2], o[3]); oo.z = pack2(o[4], o[5]); oo.w = pack2(o[6], o[7]);
	v_lshlrev_b32_e32 v240, 16, v184
	v_and_b32_e32 v241, 0xffff0000, v184
	v_lshlrev_b32_e32 v242, 16, v188
	v_and_b32_e32 v243, 0xffff0000, v188
	v_lshlrev_b32_e32 v252, 16, v192
	v_and_b32_e32 v253, 0xffff0000, v192
	v_fma_f32 v254, v130, v240, v154
	v_fma_f32 v255, v131, v241, v155
	v_fma_f32 v254, v138, v242, v254
	v_fma_f32 v255, v139, v243, v255
	v_fma_f32 v254, v146, v252, v254
	v_fma_f32 v255, v147, v253, v255
	v_mul_f32_e32 v240, 0xbfb8aa3b, v254
	v_mul_f32_e32 v241, 0xbfb8aa3b, v255
	v_exp_f32_e32 v240, v240
	v_exp_f32_e32 v241, v241
	v_add_f32_e32 v240, 1.0, v240
	v_add_f32_e32 v241, 1.0, v241
	v_rcp_f32_e32 v240, v240
	v_rcp_f32_e32 v241, v241
	v_mul_f32_e32 v254, v254, v240
	v_mul_f32_e32 v255, v255, v241
	v_mul_f32_e32 v254, v254, v14
	v_mul_f32_e32 v255, v255, v15
	v_cvt_pk_bf16_f32 v244, v254, v255
	v_lshlrev_b32_e32 v240, 16, v185
	v_and_b32_e32 v241, 0xffff0000, v185
	v_lshlrev_b32_e32 v242, 16, v189
	v_and_b32_e32 v243, 0xffff0000, v189
	v_lshlrev_b32_e32 v252, 16, v193
	v_and_b32_e32 v253, 0xffff0000, v193
	v_fma_f32 v254, v132, v240, v156
	v_fma_f32 v255, v133, v241, v157
	v_fma_f32 v254, v140, v242, v254
	v_fma_f32 v255, v141, v243, v255
	v_fma_f32 v254, v148, v252, v254
	v_fma_f32 v255, v149, v253, v255
	v_mul_f32_e32 v240, 0xbfb8aa3b, v254
	v_mul_f32_e32 v241, 0xbfb8aa3b, v255
	v_exp_f32_e32 v240, v240
	v_exp_f32_e32 v241, v241
	v_add_f32_e32 v240, 1.0, v240
	v_add_f32_e32 v241, 1.0, v241
	v_rcp_f32_e32 v240, v240
	v_rcp_f32_e32 v241, v241
	v_mul_f32_e32 v254, v254, v240
	v_mul_f32_e32 v255, v255, v241
	v_mul_f32_e32 v254, v254, v16
	v_mul_f32_e32 v255, v255, v17
	v_cvt_pk_bf16_f32 v245, v254, v255
	v_lshlrev_b32_e32 v240, 16, v186
	v_and_b32_e32 v241, 0xffff0000, v186
	v_lshlrev_b32_e32 v242, 16, v190
	v_and_b32_e32 v243, 0xffff0000, v190
	v_lshlrev_b32_e32 v252, 16, v194
	v_and_b32_e32 v253, 0xffff0000, v194
	v_fma_f32 v254, v134, v240, v158
	v_fma_f32 v255, v135, v241, v159
	v_fma_f32 v254, v142, v242, v254
	v_fma_f32 v255, v143, v243, v255
	v_fma_f32 v254, v150, v252, v254
	v_fma_f32 v255, v151, v253, v255
	v_mul_f32_e32 v240, 0xbfb8aa3b, v254
	v_mul_f32_e32 v241, 0xbfb8aa3b, v255
	v_exp_f32_e32 v240, v240
	v_exp_f32_e32 v241, v241
	v_add_f32_e32 v240, 1.0, v240
	v_add_f32_e32 v241, 1.0, v241
	v_rcp_f32_e32 v240, v240
	v_rcp_f32_e32 v241, v241
	v_mul_f32_e32 v254, v254, v240
	v_mul_f32_e32 v255, v255, v241
	v_mul_f32_e32 v254, v254, v10
	v_mul_f32_e32 v255, v255, v11
	v_cvt_pk_bf16_f32 v246, v254, v255
	v_lshlrev_b32_e32 v240, 16, v187
	v_and_b32_e32 v241, 0xffff0000, v187
	v_lshlrev_b32_e32 v242, 16, v191
	v_and_b32_e32 v243, 0xffff0000, v191
	v_lshlrev_b32_e32 v252, 16, v195
	v_and_b32_e32 v253, 0xffff0000, v195
	v_fma_f32 v254, v136, v240, v160
	v_fma_f32 v255, v137, v241, v161
	v_fma_f32 v254, v144, v242, v254
	v_fma_f32 v255, v145, v243, v255
	v_fma_f32 v254, v152, v252, v254
	v_fma_f32 v255, v153, v253, v255
	v_mul_f32_e32 v240, 0xbfb8aa3b, v254
	v_mul_f32_e32 v241, 0xbfb8aa3b, v255
	v_exp_f32_e32 v240, v240
	v_exp_f32_e32 v241, v241
	v_add_f32_e32 v240, 1.0, v240
	v_add_f32_e32 v241, 1.0, v241
	v_rcp_f32_e32 v240, v240
	v_rcp_f32_e32 v241, v241
	v_mul_f32_e32 v254, v254, v240
	v_mul_f32_e32 v255, v255, v241
	v_mul_f32_e32 v254, v254, v12
	v_mul_f32_e32 v255, v255, v13
	v_cvt_pk_bf16_f32 v247, v254, v255
	global_store_dwordx4 v[196:197], v[244:247], off offset:256
	s_waitcnt vmcnt(1)
	v_add_u32_e32 v183, 0xb0, v176
	v_and_b32_e32 v183, 0x1fff, v183
	v_cmp_eq_u32_e32 vcc, 0x1fff, v183
	v_cndmask_b32_e64 v206, v206, 0, vcc
	v_cndmask_b32_e64 v207, v207, 0, vcc
	v_cndmask_b32_e64 v208, v208, 0, vcc
	v_cndmask_b32_e64 v209, v209, 0, vcc
	v_lshlrev_b32_e32 v240, 16, v198
	v_and_b32_e32 v241, 0xffff0000, v198
	v_lshlrev_b32_e32 v242, 16, v202
	v_and_b32_e32 v243, 0xffff0000, v202
	v_lshlrev_b32_e32 v252, 16, v206
	v_and_b32_e32 v253, 0xffff0000, v206
	v_fma_f32 v254, v130, v240, v154
	v_fma_f32 v255, v131, v241, v155
	v_fma_f32 v254, v138, v242, v254
	v_fma_f32 v255, v139, v243, v255
	v_fma_f32 v254, v146, v252, v254
	v_fma_f32 v255, v147, v253, v255
	v_mul_f32_e32 v240, 0xbfb8aa3b, v254
	v_mul_f32_e32 v241, 0xbfb8aa3b, v255
	v_exp_f32_e32 v240, v240
	v_exp_f32_e32 v241, v241
	v_add_f32_e32 v240, 1.0, v240
	v_add_f32_e32 v241, 1.0, v241
	v_rcp_f32_e32 v240, v240
	v_rcp_f32_e32 v241, v241
	v_mul_f32_e32 v254, v254, v240
	v_mul_f32_e32 v255, v255, v241
	v_mul_f32_e32 v254, v254, v6
	v_mul_f32_e32 v255, v255, v7
	v_cvt_pk_bf16_f32 v248, v254, v255
	v_lshlrev_b32_e32 v240, 16, v199
	v_and_b32_e32 v241, 0xffff0000, v199
	v_lshlrev_b32_e32 v242, 16, v203
	v_and_b32_e32 v243, 0xffff0000, v203
	v_lshlrev_b32_e32 v252, 16, v207
	v_and_b32_e32 v253, 0xffff0000, v207
	v_fma_f32 v254, v132, v240, v156
	v_fma_f32 v255, v133, v241, v157
	v_fma_f32 v254, v140, v242, v254
	v_fma_f32 v255, v141, v243, v255
	v_fma_f32 v254, v148, v252, v254
	v_fma_f32 v255, v149, v253, v255
	v_mul_f32_e32 v240, 0xbfb8aa3b, v254
	v_mul_f32_e32 v241, 0xbfb8aa3b, v255
	v_exp_f32_e32 v240, v240
	v_exp_f32_e32 v241, v241
	v_add_f32_e32 v240, 1.0, v240
	v_add_f32_e32 v241, 1.0, v241
	v_rcp_f32_e32 v240, v240
	v_rcp_f32_e32 v241, v241
	v_mul_f32_e32 v254, v254, v240
	v_mul_f32_e32 v255, v255, v241
	v_mul_f32_e32 v254, v254, v8
	v_mul_f32_e32 v255, v255, v9
	v_cvt_pk_bf16_f32 v249, v254, v255
	v_lshlrev_b32_e32 v240, 16, v200
	v_and_b32_e32 v241, 0xffff0000, v200
	v_lshlrev_b32_e32 v242, 16, v204
	v_and_b32_e32 v243, 0xffff0000, v204
	v_lshlrev_b32_e32 v252, 16, v208
	v_and_b32_e32 v253, 0xffff0000, v208
	v_fma_f32 v254, v134, v240, v158
	v_fma_f32 v255, v135, v241, v159
	v_fma_f32 v254, v142, v242, v254
	v_fma_f32 v255, v143, v243, v255
	v_fma_f32 v254, v150, v252, v254
	v_fma_f32 v255, v151, v253, v255
	v_mul_f32_e32 v240, 0xbfb8aa3b, v254
	v_mul_f32_e32 v241, 0xbfb8aa3b, v255
	v_exp_f32_e32 v240, v240
	v_exp_f32_e32 v241, v241
	v_add_f32_e32 v240, 1.0, v240
	v_add_f32_e32 v241, 1.0, v241
	v_rcp_f32_e32 v240, v240
	v_rcp_f32_e32 v241, v241
	v_mul_f32_e32 v254, v254, v240
	v_mul_f32_e32 v255, v255, v241
	v_mul_f32_e32 v254, v254, v2
	v_mul_f32_e32 v255, v255, v3
	v_cvt_pk_bf16_f32 v250, v254, v255
	v_lshlrev_b32_e32 v240, 16, v201
	v_and_b32_e32 v241, 0xffff0000, v201
	v_lshlrev_b32_e32 v242, 16, v205
	v_and_b32_e32 v243, 0xffff0000, v205
	v_lshlrev_b32_e32 v252, 16, v209
	v_and_b32_e32 v253, 0xffff0000, v209
	v_fma_f32 v254, v136, v240, v160
	v_fma_f32 v255, v137, v241, v161
	v_fma_f32 v254, v144, v242, v254
	v_fma_f32 v255, v145, v243, v255
	v_fma_f32 v254, v152, v252, v254
	v_fma_f32 v255, v153, v253, v255
	v_mul_f32_e32 v240, 0xbfb8aa3b, v254
	v_mul_f32_e32 v241, 0xbfb8aa3b, v255
	v_exp_f32_e32 v240, v240
	v_exp_f32_e32 v241, v241
	v_add_f32_e32 v240, 1.0, v240
	v_add_f32_e32 v241, 1.0, v241
	v_rcp_f32_e32 v240, v240
	v_rcp_f32_e32 v241, v241
	v_mul_f32_e32 v254, v254, v240
	v_mul_f32_e32 v255, v255, v241
	v_mul_f32_e32 v254, v254, v4
	v_mul_f32_e32 v255, v255, v5
	v_cvt_pk_bf16_f32 v251, v254, v255
	global_store_dwordx4 v[220:221], v[248:251], off offset:256
	s_mov_b64 s[0:1], 0

; __global__ void __launch_bounds__(512) fwd_megakernel(Params p) {
;   cg::grid_group grid = cg::this_grid();
;   extern __shared__ __attribute__((aligned(16))) char smem[];
	.amdhsa_kernel _Z14fwd_megakernel6Params
		.amdhsa_group_segment_fixed_size 0
		.amdhsa_private_segment_fixed_size 0
		.amdhsa_kernarg_size 496
		.amdhsa_user_sgpr_count 2
		.amdhsa_user_sgpr_dispatch_ptr 0
		.amdhsa_user_sgpr_queue_ptr 0
		.amdhsa_user_sgpr_kernarg_segment_ptr 1
		.amdhsa_user_sgpr_dispatch_id 0
		.amdhsa_user_sgpr_kernarg_preload_length 0
		.amdhsa_user_sgpr_kernarg_preload_offset 0
		.amdhsa_user_sgpr_private_segment_size 0
		.amdhsa_uses_dynamic_stack 0
		.amdhsa_enable_private_segment 0
		.amdhsa_system_sgpr_workgroup_id_x 1
		.amdhsa_system_sgpr_workgroup_id_y 0
		.amdhsa_system_sgpr_workgroup_id_z 0
		.amdhsa_system_sgpr_workgroup_info 0
		.amdhsa_system_vgpr_workitem_id 2
		.amdhsa_next_free_vgpr 256
		.amdhsa_next_free_sgpr 102
		.amdhsa_accum_offset 256
		.amdhsa_reserve_vcc 1
		.amdhsa_float_round_mode_32 0
		.amdhsa_float_round_mode_16_64 0
		.amdhsa_float_denorm_mode_32 3
		.amdhsa_float_denorm_mode_16_64 3
		.amdhsa_dx10_clamp 1
		.amdhsa_ieee_mode 1
		.amdhsa_fp16_overflow 0
		.amdhsa_tg_split 0
		.amdhsa_exception_fp_ieee_invalid_op 0
		.amdhsa_exception_fp_denorm_src 0
		.amdhsa_exception_fp_ieee_div_zero 0
		.amdhsa_exception_fp_ieee_overflow 0
		.amdhsa_exception_fp_ieee_underflow 0
		.amdhsa_exception_fp_ieee_inexact 0
		.amdhsa_exception_int_div_zero 0
	.end_amdhsa_kernel

amdhsa.kernels:
  - .agpr_count:     0
    .args:
      - .offset:         0
        .size:           240
        .value_kind:     by_value
      - .offset:         240
        .size:           4
        .value_kind:     hidden_block_count_x
      - .offset:         244
        .size:           4
        .value_kind:     hidden_block_count_y
      - .offset:         248
        .size:           4
        .value_kind:     hidden_block_count_z
      - .offset:         252
        .size:           2
        .value_kind:     hidden_group_size_x
      - .offset:         254
        .size:           2
        .value_kind:     hidden_group_size_y
      - .offset:         256
        .size:           2
        .value_kind:     hidden_group_size_z
      - .offset:         258
        .size:           2
        .value_kind:     hidden_remainder_x
      - .offset:         260
        .size:           2
        .value_kind:     hidden_remainder_y
      - .offset:         262
        .size:           2
        .value_kind:     hidden_remainder_z
      - .offset:         280
        .size:           8
        .value_kind:     hidden_global_offset_x
      - .offset:         288
        .size:           8
        .value_kind:     hidden_global_offset_y
      - .offset:         296
        .size:           8
        .value_kind:     hidden_global_offset_z
      - .offset:         304
        .size:           2
        .value_kind:     hidden_grid_dims
      - .offset:         328
        .size:           8
        .value_kind:     hidden_multigrid_sync_arg
      - .offset:         360
        .size:           4
        .value_kind:     hidden_dynamic_lds_size
    .group_segment_fixed_size: 0
    .kernarg_segment_align: 8
    .kernarg_segment_size: 496
    .language:       OpenCL C
    .language_version:
      - 2
      - 0
    .max_flat_workgroup_size: 512
    .name:           _Z14fwd_megakernel6Params
    .private_segment_fixed_size: 0
    .sgpr_count:     108
    .sgpr_spill_count: 213
    .symbol:         _Z14fwd_megakernel6Params.kd
    .uniform_work_group_size: 1
    .uses_dynamic_stack: false
    .vgpr_count:     256
    .vgpr_spill_count: 0
    .wavefront_size: 64
